# v40: + P2/P7/P9 epilogue of the split-K tail row tile: waves 4-7 skip, waves 0-3 stop after the valid 64 rows
# speedup vs baseline: 1.1724x; 1.0128x over previous
.LBB0_658:
	s_and_b64 vcc, exec, s[2:3]
	s_cbranch_vccz .LBB0_596
	s_cmpk_ge_i32 s9, 0x4000
	s_cselect_b32 s32, 1, 0
	s_cbranch_scc0 .Lrt0_f
	v_readfirstlane_b32 s98, v208
	s_bitcmp1_b32 s98, 8
	s_cbranch_scc0 .Lrt0_f
	s_waitcnt vmcnt(0)
	s_branch .LBB0_596
.Lrt0_f:
	v_mov_b32_e32 v172, v208
	s_nop 0
	v_ashrrev_i32_e32 v0, 1, v172
	v_and_b32_e32 v0, 0xffffff80, v0
	s_waitcnt vmcnt(7)
	v_lshrrev_b32_e32 v130, 3, v172
	v_and_b32_e32 v173, 4, v130
	v_add_u32_e32 v174, s9, v0
	s_waitcnt vmcnt(6)
	v_or_b32_e32 v136, v174, v173
	v_min_i32_e32 v0, 0x403f, v136
	v_mul_hi_i32 v130, v0, s30
	v_lshrrev_b32_e32 v131, 31, v130
	v_ashrrev_i32_e32 v130, 11, v130
	v_add_u32_e32 v130, v130, v131
	v_mad_i32_i24 v0, v130, s31, v0
	v_cmp_lt_i32_e32 vcc, 15, v0
	s_and_saveexec_b64 s[0:1], vcc
	s_xor_b64 s[0:1], exec, s[0:1]
	v_lshlrev_b32_e32 v130, 12, v130
	v_add3_u32 v130, v130, v0, -16
	v_ashrrev_i32_e32 v131, 31, v130
	v_lshlrev_b64 v[130:131], 12, v[130:131]
	v_lshl_add_u64 v[132:133], s[56:57], 0, v[130:131]
	s_andn2_saveexec_b64 s[0:1], s[0:1]
	v_lshlrev_b32_e32 v130, 10, v0
	v_ashrrev_i32_e32 v131, 31, v130
	v_lshl_add_u64 v[132:133], v[130:131], 2, s[58:59]
	s_or_b64 exec, exec, s[0:1]
	v_bfe_u32 v0, v172, 6, 2
	v_and_b32_e32 v175, 31, v172
	v_lshlrev_b32_e32 v130, 6, v0
	v_or3_b32 v130, v130, s8, v175
	v_ashrrev_i32_e32 v131, 31, v130
	v_lshl_add_u64 v[132:133], v[130:131], 2, v[132:133]
	global_load_dword v176, v[132:133], off
	global_load_dword v177, v[132:133], off offset:128
	v_or_b32_e32 v166, 1, v136
	v_min_i32_e32 v132, 0x403f, v166
	v_mul_hi_i32 v133, v132, s30
	v_lshrrev_b32_e32 v134, 31, v133
	v_ashrrev_i32_e32 v133, 11, v133
	v_add_u32_e32 v135, v133, v134
	v_mad_i32_i24 v134, v135, s31, v132
	v_cmp_lt_i32_e32 vcc, 15, v134
	s_and_saveexec_b64 s[0:1], vcc
	s_xor_b64 s[0:1], exec, s[0:1]
	v_lshlrev_b32_e32 v132, 12, v135
	v_add3_u32 v132, v132, v134, -16
	v_ashrrev_i32_e32 v133, 31, v132
	v_lshlrev_b64 v[132:133], 12, v[132:133]
	v_lshl_add_u64 v[132:133], s[56:57], 0, v[132:133]
	s_andn2_saveexec_b64 s[0:1], s[0:1]
	v_lshlrev_b32_e32 v132, 10, v134
	v_ashrrev_i32_e32 v133, 31, v132
	v_lshl_add_u64 v[132:133], v[132:133], 2, s[58:59]
	s_or_b64 exec, exec, s[0:1]
	v_lshl_add_u64 v[132:133], v[130:131], 2, v[132:133]
	global_load_dword v181, v[132:133], off
	global_load_dword v182, v[132:133], off offset:128
	v_or_b32_e32 v164, 2, v136
	v_min_i32_e32 v132, 0x403f, v164
	v_mul_hi_i32 v133, v132, s30
	v_lshrrev_b32_e32 v134, 31, v133
	v_ashrrev_i32_e32 v133, 11, v133
	v_add_u32_e32 v135, v133, v134
	v_mad_i32_i24 v134, v135, s31, v132
	v_cmp_lt_i32_e32 vcc, 15, v134
	s_and_saveexec_b64 s[0:1], vcc
	s_xor_b64 s[0:1], exec, s[0:1]
	v_lshlrev_b32_e32 v132, 12, v135
	v_add3_u32 v132, v132, v134, -16
	v_ashrrev_i32_e32 v133, 31, v132
	v_lshlrev_b64 v[132:133], 12, v[132:133]
	v_lshl_add_u64 v[132:133], s[56:57], 0, v[132:133]
	s_andn2_saveexec_b64 s[0:1], s[0:1]
	v_lshlrev_b32_e32 v132, 10, v134
	v_ashrrev_i32_e32 v133, 31, v132
	v_lshl_add_u64 v[132:133], v[132:133], 2, s[58:59]
	s_or_b64 exec, exec, s[0:1]
	v_lshl_add_u64 v[132:133], v[130:131], 2, v[132:133]
	global_load_dword v183, v[132:133], off
	global_load_dword v184, v[132:133], off offset:128
	v_or_b32_e32 v162, 3, v136
	v_min_i32_e32 v132, 0x403f, v162
	v_mul_hi_i32 v133, v132, s30
	v_lshrrev_b32_e32 v134, 31, v133
	v_ashrrev_i32_e32 v133, 11, v133
	v_add_u32_e32 v135, v133, v134
	v_mad_i32_i24 v134, v135, s31, v132
	v_cmp_lt_i32_e32 vcc, 15, v134
	s_and_saveexec_b64 s[0:1], vcc
	s_xor_b64 s[0:1], exec, s[0:1]
	v_lshlrev_b32_e32 v132, 12, v135
	v_add3_u32 v132, v132, v134, -16
	v_ashrrev_i32_e32 v133, 31, v132
	v_lshlrev_b64 v[132:133], 12, v[132:133]
	v_lshl_add_u64 v[132:133], s[56:57], 0, v[132:133]
	s_andn2_saveexec_b64 s[0:1], s[0:1]
	v_lshlrev_b32_e32 v132, 10, v134
	v_ashrrev_i32_e32 v133, 31, v132
	v_lshl_add_u64 v[132:133], v[132:133], 2, s[58:59]
	s_or_b64 exec, exec, s[0:1]
	v_lshl_add_u64 v[132:133], v[130:131], 2, v[132:133]
	global_load_dword v185, v[132:133], off
	global_load_dword v186, v[132:133], off offset:128
	s_waitcnt vmcnt(13)
	v_or_b32_e32 v160, 8, v136
	v_min_i32_e32 v132, 0x403f, v160
	v_mul_hi_i32 v133, v132, s30
	v_lshrrev_b32_e32 v134, 31, v133
	v_ashrrev_i32_e32 v133, 11, v133
	v_add_u32_e32 v135, v133, v134
	v_mad_i32_i24 v134, v135, s31, v132
	v_cmp_lt_i32_e32 vcc, 15, v134
	s_and_saveexec_b64 s[0:1], vcc
	s_xor_b64 s[0:1], exec, s[0:1]
	v_lshlrev_b32_e32 v132, 12, v135
	v_add3_u32 v132, v132, v134, -16
	v_ashrrev_i32_e32 v133, 31, v132
	v_lshlrev_b64 v[132:133], 12, v[132:133]
	v_lshl_add_u64 v[132:133], s[56:57], 0, v[132:133]
	s_andn2_saveexec_b64 s[0:1], s[0:1]
	v_lshlrev_b32_e32 v132, 10, v134
	v_ashrrev_i32_e32 v133, 31, v132
	v_lshl_add_u64 v[132:133], v[132:133], 2, s[58:59]
	s_or_b64 exec, exec, s[0:1]
	v_lshl_add_u64 v[132:133], v[130:131], 2, v[132:133]
	global_load_dword v187, v[132:133], off
	global_load_dword v188, v[132:133], off offset:128
	v_or_b32_e32 v158, 9, v136
	v_min_i32_e32 v132, 0x403f, v158
	v_mul_hi_i32 v133, v132, s30
	v_lshrrev_b32_e32 v134, 31, v133
	v_ashrrev_i32_e32 v133, 11, v133
	v_add_u32_e32 v135, v133, v134
	v_mad_i32_i24 v134, v135, s31, v132
	v_cmp_lt_i32_e32 vcc, 15, v134
	s_and_saveexec_b64 s[0:1], vcc
	s_xor_b64 s[0:1], exec, s[0:1]
	v_lshlrev_b32_e32 v132, 12, v135
	v_add3_u32 v132, v132, v134, -16
	v_ashrrev_i32_e32 v133, 31, v132
	v_lshlrev_b64 v[132:133], 12, v[132:133]
	v_lshl_add_u64 v[132:133], s[56:57], 0, v[132:133]
	s_andn2_saveexec_b64 s[0:1], s[0:1]
	v_lshlrev_b32_e32 v132, 10, v134
	v_ashrrev_i32_e32 v133, 31, v132
	v_lshl_add_u64 v[132:133], v[132:133], 2, s[58:59]
	s_or_b64 exec, exec, s[0:1]
	v_lshl_add_u64 v[132:133], v[130:131], 2, v[132:133]
	global_load_dword v189, v[132:133], off
	global_load_dword v190, v[132:133], off offset:128
	s_waitcnt vmcnt(12)
	v_or_b32_e32 v156, 10, v136
	v_min_i32_e32 v132, 0x403f, v156
	v_mul_hi_i32 v133, v132, s30
	v_lshrrev_b32_e32 v134, 31, v133
	v_ashrrev_i32_e32 v133, 11, v133
	v_add_u32_e32 v135, v133, v134
	v_mad_i32_i24 v134, v135, s31, v132
	v_cmp_lt_i32_e32 vcc, 15, v134
	s_and_saveexec_b64 s[0:1], vcc
	s_xor_b64 s[0:1], exec, s[0:1]
	v_lshlrev_b32_e32 v132, 12, v135
	v_add3_u32 v132, v132, v134, -16
	v_ashrrev_i32_e32 v133, 31, v132
	v_lshlrev_b64 v[132:133], 12, v[132:133]
	v_lshl_add_u64 v[132:133], s[56:57], 0, v[132:133]
	s_andn2_saveexec_b64 s[0:1], s[0:1]
	v_lshlrev_b32_e32 v132, 10, v134
	v_ashrrev_i32_e32 v133, 31, v132
	v_lshl_add_u64 v[132:133], v[132:133], 2, s[58:59]
	s_or_b64 exec, exec, s[0:1]
	v_lshl_add_u64 v[132:133], v[130:131], 2, v[132:133]
	global_load_dword v191, v[132:133], off
	global_load_dword v192, v[132:133], off offset:128
	v_or_b32_e32 v154, 11, v136
	v_min_i32_e32 v132, 0x403f, v154
	v_mul_hi_i32 v133, v132, s30
	v_lshrrev_b32_e32 v134, 31, v133
	v_ashrrev_i32_e32 v133, 11, v133
	v_add_u32_e32 v135, v133, v134
	v_mad_i32_i24 v134, v135, s31, v132
	v_cmp_lt_i32_e32 vcc, 15, v134
	s_and_saveexec_b64 s[0:1], vcc
	s_xor_b64 s[0:1], exec, s[0:1]
	v_lshlrev_b32_e32 v132, 12, v135
	v_add3_u32 v132, v132, v134, -16
	v_ashrrev_i32_e32 v133, 31, v132
	v_lshlrev_b64 v[132:133], 12, v[132:133]
	v_lshl_add_u64 v[132:133], s[56:57], 0, v[132:133]
	s_andn2_saveexec_b64 s[0:1], s[0:1]
	v_lshlrev_b32_e32 v132, 10, v134
	v_ashrrev_i32_e32 v133, 31, v132
	v_lshl_add_u64 v[132:133], v[132:133], 2, s[58:59]
	s_or_b64 exec, exec, s[0:1]
	v_lshl_add_u64 v[132:133], v[130:131], 2, v[132:133]
	global_load_dword v193, v[132:133], off
	global_load_dword v194, v[132:133], off offset:128
	v_or_b32_e32 v152, 16, v136
	v_min_i32_e32 v132, 0x403f, v152
	v_mul_hi_i32 v133, v132, s30
	v_lshrrev_b32_e32 v134, 31, v133
	v_ashrrev_i32_e32 v133, 11, v133
	v_add_u32_e32 v135, v133, v134
	v_mad_i32_i24 v134, v135, s31, v132
	v_cmp_lt_i32_e32 vcc, 15, v134
	s_and_saveexec_b64 s[0:1], vcc
	s_xor_b64 s[0:1], exec, s[0:1]
	v_lshlrev_b32_e32 v132, 12, v135
	v_add3_u32 v132, v132, v134, -16
	v_ashrrev_i32_e32 v133, 31, v132
	v_lshlrev_b64 v[132:133], 12, v[132:133]
	v_lshl_add_u64 v[132:133], s[56:57], 0, v[132:133]
	s_andn2_saveexec_b64 s[0:1], s[0:1]
	v_lshlrev_b32_e32 v132, 10, v134
	v_ashrrev_i32_e32 v133, 31, v132
	v_lshl_add_u64 v[132:133], v[132:133], 2, s[58:59]
	s_or_b64 exec, exec, s[0:1]
	v_lshl_add_u64 v[132:133], v[130:131], 2, v[132:133]
	global_load_dword v195, v[132:133], off
	global_load_dword v196, v[132:133], off offset:128
	v_or_b32_e32 v150, 17, v136
	v_min_i32_e32 v132, 0x403f, v150
	v_mul_hi_i32 v133, v132, s30
	v_lshrrev_b32_e32 v134, 31, v133
	v_ashrrev_i32_e32 v133, 11, v133
	v_add_u32_e32 v135, v133, v134
	v_mad_i32_i24 v134, v135, s31, v132
	v_cmp_lt_i32_e32 vcc, 15, v134
	s_and_saveexec_b64 s[0:1], vcc
	s_xor_b64 s[0:1], exec, s[0:1]
	v_lshlrev_b32_e32 v132, 12, v135
	v_add3_u32 v132, v132, v134, -16
	v_ashrrev_i32_e32 v133, 31, v132
	v_lshlrev_b64 v[132:133], 12, v[132:133]
	v_lshl_add_u64 v[132:133], s[56:57], 0, v[132:133]
	s_andn2_saveexec_b64 s[0:1], s[0:1]
	v_lshlrev_b32_e32 v132, 10, v134
	v_ashrrev_i32_e32 v133, 31, v132
	v_lshl_add_u64 v[132:133], v[132:133], 2, s[58:59]
	s_or_b64 exec, exec, s[0:1]
	v_lshl_add_u64 v[132:133], v[130:131], 2, v[132:133]
	global_load_dword v197, v[132:133], off
	global_load_dword v198, v[132:133], off offset:128
	v_or_b32_e32 v148, 18, v136
	v_min_i32_e32 v132, 0x403f, v148
	v_mul_hi_i32 v133, v132, s30
	v_lshrrev_b32_e32 v134, 31, v133
	v_ashrrev_i32_e32 v133, 11, v133
	v_add_u32_e32 v135, v133, v134
	v_mad_i32_i24 v134, v135, s31, v132
	v_cmp_lt_i32_e32 vcc, 15, v134
	s_and_saveexec_b64 s[0:1], vcc
	s_xor_b64 s[0:1], exec, s[0:1]
	v_lshlrev_b32_e32 v132, 12, v135
	v_add3_u32 v132, v132, v134, -16
	v_ashrrev_i32_e32 v133, 31, v132
	v_lshlrev_b64 v[132:133], 12, v[132:133]
	v_lshl_add_u64 v[132:133], s[56:57], 0, v[132:133]
	s_andn2_saveexec_b64 s[0:1], s[0:1]
	v_lshlrev_b32_e32 v132, 10, v134
	v_ashrrev_i32_e32 v133, 31, v132
	v_lshl_add_u64 v[132:133], v[132:133], 2, s[58:59]
	s_or_b64 exec, exec, s[0:1]
	v_lshl_add_u64 v[132:133], v[130:131], 2, v[132:133]
	global_load_dword v199, v[132:133], off
	global_load_dword v200, v[132:133], off offset:128
	v_or_b32_e32 v146, 19, v136
	v_min_i32_e32 v132, 0x403f, v146
	v_mul_hi_i32 v133, v132, s30
	v_lshrrev_b32_e32 v134, 31, v133
	v_ashrrev_i32_e32 v133, 11, v133
	v_add_u32_e32 v135, v133, v134
	v_mad_i32_i24 v134, v135, s31, v132
	v_cmp_lt_i32_e32 vcc, 15, v134
	s_and_saveexec_b64 s[0:1], vcc
	s_xor_b64 s[0:1], exec, s[0:1]
	v_lshlrev_b32_e32 v132, 12, v135
	v_add3_u32 v132, v132, v134, -16
	v_ashrrev_i32_e32 v133, 31, v132
	v_lshlrev_b64 v[132:133], 12, v[132:133]
	v_lshl_add_u64 v[132:133], s[56:57], 0, v[132:133]
	s_andn2_saveexec_b64 s[0:1], s[0:1]
	v_lshlrev_b32_e32 v132, 10, v134
	v_ashrrev_i32_e32 v133, 31, v132
	v_lshl_add_u64 v[132:133], v[132:133], 2, s[58:59]
	s_or_b64 exec, exec, s[0:1]
	v_lshl_add_u64 v[132:133], v[130:131], 2, v[132:133]
	global_load_dword v201, v[132:133], off
	global_load_dword v202, v[132:133], off offset:128
	v_or_b32_e32 v144, 24, v136
	v_min_i32_e32 v132, 0x403f, v144
	v_mul_hi_i32 v133, v132, s30
	v_lshrrev_b32_e32 v134, 31, v133
	v_ashrrev_i32_e32 v133, 11, v133
	v_add_u32_e32 v135, v133, v134
	v_mad_i32_i24 v134, v135, s31, v132
	v_cmp_lt_i32_e32 vcc, 15, v134
	s_and_saveexec_b64 s[0:1], vcc
	s_xor_b64 s[0:1], exec, s[0:1]
	v_lshlrev_b32_e32 v132, 12, v135
	v_add3_u32 v132, v132, v134, -16
	v_ashrrev_i32_e32 v133, 31, v132
	v_lshlrev_b64 v[132:133], 12, v[132:133]
	v_lshl_add_u64 v[132:133], s[56:57], 0, v[132:133]
	s_andn2_saveexec_b64 s[0:1], s[0:1]
	v_lshlrev_b32_e32 v132, 10, v134
	v_ashrrev_i32_e32 v133, 31, v132
	v_lshl_add_u64 v[132:133], v[132:133], 2, s[58:59]
	s_or_b64 exec, exec, s[0:1]
	v_lshl_add_u64 v[132:133], v[130:131], 2, v[132:133]
	global_load_dword v203, v[132:133], off
	global_load_dword v204, v[132:133], off offset:128
	v_or_b32_e32 v142, 25, v136
	v_min_i32_e32 v132, 0x403f, v142
	v_mul_hi_i32 v133, v132, s30
	v_lshrrev_b32_e32 v134, 31, v133
	v_ashrrev_i32_e32 v133, 11, v133
	v_add_u32_e32 v135, v133, v134
	v_mad_i32_i24 v134, v135, s31, v132
	v_cmp_lt_i32_e32 vcc, 15, v134
	s_and_saveexec_b64 s[0:1], vcc
	s_xor_b64 s[0:1], exec, s[0:1]
	v_lshlrev_b32_e32 v132, 12, v135
	v_add3_u32 v132, v132, v134, -16
	v_ashrrev_i32_e32 v133, 31, v132
	v_lshlrev_b64 v[132:133], 12, v[132:133]
	v_lshl_add_u64 v[132:133], s[56:57], 0, v[132:133]
	s_andn2_saveexec_b64 s[0:1], s[0:1]
	v_lshlrev_b32_e32 v132, 10, v134
	v_ashrrev_i32_e32 v133, 31, v132
	v_lshl_add_u64 v[132:133], v[132:133], 2, s[58:59]
	s_or_b64 exec, exec, s[0:1]
	v_lshl_add_u64 v[132:133], v[130:131], 2, v[132:133]
	global_load_dword v205, v[132:133], off
	global_load_dword v206, v[132:133], off offset:128
	v_or_b32_e32 v140, 26, v136
	v_min_i32_e32 v132, 0x403f, v140
	v_mul_hi_i32 v133, v132, s30
	v_lshrrev_b32_e32 v134, 31, v133
	v_ashrrev_i32_e32 v133, 11, v133
	v_add_u32_e32 v135, v133, v134
	v_mad_i32_i24 v134, v135, s31, v132
	v_cmp_lt_i32_e32 vcc, 15, v134
	s_and_saveexec_b64 s[0:1], vcc
	s_xor_b64 s[0:1], exec, s[0:1]
	v_lshlrev_b32_e32 v132, 12, v135
	v_add3_u32 v132, v132, v134, -16
	v_ashrrev_i32_e32 v133, 31, v132
	v_lshlrev_b64 v[132:133], 12, v[132:133]
	v_lshl_add_u64 v[132:133], s[56:57], 0, v[132:133]
	s_andn2_saveexec_b64 s[0:1], s[0:1]
	v_lshlrev_b32_e32 v132, 10, v134
	v_ashrrev_i32_e32 v133, 31, v132
	v_lshl_add_u64 v[132:133], v[132:133], 2, s[58:59]
	s_or_b64 exec, exec, s[0:1]
	v_lshl_add_u64 v[132:133], v[130:131], 2, v[132:133]
	global_load_dword v207, v[132:133], off
	global_load_dword v210, v[132:133], off offset:128
	v_or_b32_e32 v138, 27, v136
	v_min_i32_e32 v132, 0x403f, v138
	v_mul_hi_i32 v133, v132, s30
	v_lshrrev_b32_e32 v134, 31, v133
	v_ashrrev_i32_e32 v133, 11, v133
	v_add_u32_e32 v135, v133, v134
	v_mad_i32_i24 v134, v135, s31, v132
	v_cmp_lt_i32_e32 vcc, 15, v134
	s_and_saveexec_b64 s[0:1], vcc
	s_xor_b64 s[0:1], exec, s[0:1]
	v_lshlrev_b32_e32 v132, 12, v135
	v_add3_u32 v132, v132, v134, -16
	v_ashrrev_i32_e32 v133, 31, v132
	v_lshlrev_b64 v[132:133], 12, v[132:133]
	v_lshl_add_u64 v[132:133], s[56:57], 0, v[132:133]
	s_andn2_saveexec_b64 s[0:1], s[0:1]
	v_lshlrev_b32_e32 v132, 10, v134
	v_ashrrev_i32_e32 v133, 31, v132
	v_lshl_add_u64 v[132:133], v[132:133], 2, s[58:59]
	s_or_b64 exec, exec, s[0:1]
	v_lshl_add_u64 v[132:133], v[130:131], 2, v[132:133]
	global_load_dword v211, v[132:133], off
	global_load_dword v212, v[132:133], off offset:128
	v_cmp_gt_i32_e32 vcc, s34, v136
	s_nop 1
	v_cndmask_b32_e32 v132, v179, v136, vcc
	v_mul_hi_i32 v133, v132, s30
	v_lshrrev_b32_e32 v134, 31, v133
	v_ashrrev_i32_e32 v133, 11, v133
	v_add_u32_e32 v134, v133, v134
	v_mad_i32_i24 v135, v134, s31, v132
	v_cmp_lt_i32_e64 s[0:1], 15, v135
	s_and_saveexec_b64 s[2:3], s[0:1]
	s_xor_b64 s[0:1], exec, s[2:3]
	v_lshlrev_b32_e32 v132, 12, v134
	v_add3_u32 v132, v132, v135, -16
	v_ashrrev_i32_e32 v133, 31, v132
	v_lshlrev_b64 v[132:133], 12, v[132:133]
	v_lshl_add_u64 v[132:133], s[88:89], 0, v[132:133]
	s_andn2_saveexec_b64 s[0:1], s[0:1]
	v_lshlrev_b32_e32 v132, 14, v134
	v_lshl_add_u32 v132, v135, 10, v132
	v_ashrrev_i32_e32 v133, 31, v132
	v_lshl_add_u64 v[132:133], v[132:133], 2, s[12:13]
	s_or_b64 exec, exec, s[0:1]
	v_ashrrev_i32_e32 v137, 31, v136
	v_lshlrev_b64 v[134:135], 11, v[136:137]
	v_lshl_add_u64 v[168:169], s[62:63], 0, v[134:135]
	v_lshlrev_b64 v[134:135], 2, v[130:131]
	s_waitcnt vmcnt(31)
	v_fmac_f32_e32 v176, 0.5, v114
	v_lshl_add_u64 v[168:169], v[130:131], 1, v[168:169]
	v_lshl_add_u64 v[170:171], v[132:133], 0, v[134:135]
	v_lshl_add_u64 v[132:133], s[68:69], 0, v[134:135]
	global_load_dword v242, v[132:133], off
	global_load_dword v243, v[132:133], off offset:128
	s_waitcnt vmcnt(0)
	s_and_saveexec_b64 s[0:1], vcc
	s_cbranch_execz .LBB0_729
	global_store_dword v[170:171], v176, off
	v_mul_f32_e32 v114, v176, v242
	v_cvt_pk_bf16_f32 v114, v114, s0
	global_store_short v[168:169], v114, off

.LBB0_1043:
	s_or_b64 exec, exec, s[0:1]
	v_lshlrev_b32_e32 v66, 1, v175
	v_lshlrev_b32_e32 v103, 1, v172
	v_and_b32_e32 v66, 32, v66
	v_and_b32_e32 v103, 24, v103
	v_and_b32_e32 v104, 3, v172
	v_or3_b32 v66, v104, v103, v66
	v_and_b32_e32 v104, 64, v180
	v_xor_b32_e32 v103, 16, v180
	v_add_u32_e32 v108, 64, v104
	v_mul_f32_e32 v81, v140, v140
	v_mul_f32_e32 v97, v177, v177
	v_and_b32_e32 v98, 16, v172
	v_cmp_lt_i32_e32 vcc, v103, v108
	v_fmac_f32_e32 v81, v137, v137
	v_fmac_f32_e32 v97, v176, v176
	v_cndmask_b32_e32 v103, v180, v103, vcc
	v_cmp_eq_u32_e32 vcc, 0, v98
	v_lshlrev_b32_e32 v104, 2, v103
	v_mul_f32_e32 v77, v148, v148
	v_cndmask_b32_e32 v98, v97, v81, vcc
	ds_bpermute_b32 v98, v104, v98
	v_mul_f32_e32 v78, v146, v146
	v_mul_f32_e32 v80, v142, v142
	v_mul_f32_e32 v93, v188, v188
	v_mul_f32_e32 v94, v186, v186
	v_mul_f32_e32 v96, v182, v182
	v_mul_f32_e32 v71, v160, v160
	v_mul_f32_e32 v72, v158, v158
	v_mul_f32_e32 v74, v154, v154
	v_mul_f32_e32 v75, v152, v152
	v_mul_f32_e32 v76, v150, v150
	v_fmac_f32_e32 v77, v147, v147
	v_fmac_f32_e32 v78, v145, v145
	v_mul_f32_e32 v79, v144, v144
	v_fmac_f32_e32 v80, v141, v141
	v_mul_f32_e32 v87, v200, v200
	v_mul_f32_e32 v88, v198, v198
	v_mul_f32_e32 v90, v194, v194
	v_mul_f32_e32 v91, v192, v192
	v_mul_f32_e32 v92, v190, v190
	v_fmac_f32_e32 v93, v187, v187
	v_fmac_f32_e32 v94, v185, v185
	v_mul_f32_e32 v95, v184, v184
	v_fmac_f32_e32 v96, v181, v181
	v_cndmask_b32_e32 v81, v81, v97, vcc
	v_mul_f32_e32 v68, v168, v168
	v_mul_f32_e32 v69, v164, v164
	v_mul_f32_e32 v70, v162, v162
	v_fmac_f32_e32 v71, v159, v159
	v_fmac_f32_e32 v72, v157, v157
	v_mul_f32_e32 v73, v156, v156
	v_fmac_f32_e32 v74, v153, v153
	v_fmac_f32_e32 v75, v151, v151
	v_fmac_f32_e32 v76, v149, v149
	v_fmac_f32_e32 v79, v143, v143
	v_mul_f32_e32 v84, v206, v206
	v_mul_f32_e32 v85, v204, v204
	v_mul_f32_e32 v86, v202, v202
	v_fmac_f32_e32 v87, v199, v199
	v_fmac_f32_e32 v88, v197, v197
	v_mul_f32_e32 v89, v196, v196
	v_fmac_f32_e32 v90, v193, v193
	v_fmac_f32_e32 v91, v191, v191
	v_fmac_f32_e32 v92, v189, v189
	v_fmac_f32_e32 v95, v183, v183
	s_waitcnt lgkmcnt(0)
	v_add_f32_e32 v81, v81, v98
	v_cndmask_b32_e32 v97, v96, v80, vcc
	v_cndmask_b32_e32 v98, v94, v78, vcc
	v_cndmask_b32_e32 v78, v78, v94, vcc
	v_cndmask_b32_e32 v94, v93, v77, vcc
	v_mul_f32_e32 v67, v170, v170
	v_fmac_f32_e32 v68, v167, v167
	v_fmac_f32_e32 v69, v163, v163
	v_fmac_f32_e32 v70, v161, v161
	v_fmac_f32_e32 v73, v155, v155
	v_mul_f32_e32 v83, v210, v210
	v_fmac_f32_e32 v84, v205, v205
	v_fmac_f32_e32 v85, v203, v203
	v_fmac_f32_e32 v86, v201, v201
	v_fmac_f32_e32 v89, v195, v195
	v_cndmask_b32_e32 v80, v80, v96, vcc
	ds_bpermute_b32 v96, v104, v97
	v_cndmask_b32_e32 v97, v95, v79, vcc
	v_cndmask_b32_e32 v79, v79, v95, vcc
	v_cndmask_b32_e32 v77, v77, v93, vcc
	ds_bpermute_b32 v93, v104, v94
	v_cndmask_b32_e32 v94, v92, v76, vcc
	v_cndmask_b32_e32 v95, v91, v75, vcc
	v_cndmask_b32_e32 v76, v76, v92, vcc
	v_cndmask_b32_e32 v75, v75, v91, vcc
	v_cndmask_b32_e32 v91, v90, v74, vcc
	v_cndmask_b32_e32 v92, v88, v72, vcc
	v_cndmask_b32_e32 v72, v72, v88, vcc
	v_cndmask_b32_e32 v88, v87, v71, vcc
	v_fmac_f32_e32 v67, v169, v169
	v_mul_f32_e32 v82, v212, v212
	v_fmac_f32_e32 v83, v207, v207
	v_mul_f32_e32 v103, v166, v166
	v_cndmask_b32_e32 v74, v74, v90, vcc
	ds_bpermute_b32 v90, v104, v91
	v_cndmask_b32_e32 v91, v89, v73, vcc
	v_cndmask_b32_e32 v73, v73, v89, vcc
	v_cndmask_b32_e32 v71, v71, v87, vcc
	ds_bpermute_b32 v87, v104, v88
	v_cndmask_b32_e32 v88, v86, v70, vcc
	v_cndmask_b32_e32 v89, v85, v69, vcc
	v_cndmask_b32_e32 v69, v69, v85, vcc
	v_cndmask_b32_e32 v85, v84, v68, vcc
	v_fmac_f32_e32 v82, v211, v211
	v_fmac_f32_e32 v103, v165, v165
	ds_bpermute_b32 v97, v104, v97
	ds_bpermute_b32 v98, v104, v98
	ds_bpermute_b32 v91, v104, v91
	ds_bpermute_b32 v88, v104, v88
	v_cndmask_b32_e32 v68, v68, v84, vcc
	ds_bpermute_b32 v84, v104, v85
	v_cndmask_b32_e32 v85, v83, v67, vcc
	ds_bpermute_b32 v94, v104, v94
	ds_bpermute_b32 v95, v104, v95
	ds_bpermute_b32 v92, v104, v92
	ds_bpermute_b32 v89, v104, v89
	v_cndmask_b32_e32 v70, v70, v86, vcc
	ds_bpermute_b32 v85, v104, v85
	v_cndmask_b32_e32 v86, v82, v103, vcc
	s_lshl_b32 s0, s4, 2
	ds_bpermute_b32 v86, v104, v86
	s_ashr_i32 s1, s0, 31
	v_cndmask_b32_e32 v67, v67, v83, vcc
	v_xor_b32_e32 v83, 8, v180
	v_and_b32_e32 v99, 8, v172
	s_lshl_b64 s[8:9], s[0:1], 2
	v_cmp_lt_i32_e64 s[0:1], v83, v108
	s_waitcnt lgkmcnt(10)
	v_add_f32_e32 v79, v79, v97
	s_waitcnt lgkmcnt(9)
	v_add_f32_e32 v78, v78, v98
	s_waitcnt lgkmcnt(8)
	v_add_f32_e32 v73, v73, v91
	v_add_f32_e32 v71, v71, v87
	s_waitcnt lgkmcnt(7)
	v_add_f32_e32 v70, v70, v88
	v_cndmask_b32_e64 v83, v180, v83, s[0:1]
	v_cmp_eq_u32_e64 s[2:3], 0, v99
	v_add_f32_e32 v80, v80, v96
	v_add_f32_e32 v77, v77, v93
	s_waitcnt lgkmcnt(5)
	v_add_f32_e32 v76, v76, v94
	s_waitcnt lgkmcnt(4)
	v_add_f32_e32 v75, v75, v95
	s_waitcnt lgkmcnt(3)
	v_add_f32_e32 v72, v72, v92
	s_waitcnt lgkmcnt(2)
	v_add_f32_e32 v69, v69, v89
	v_add_f32_e32 v68, v68, v84
	s_waitcnt lgkmcnt(1)
	v_add_f32_e32 v67, v67, v85
	v_cndmask_b32_e32 v82, v103, v82, vcc
	v_lshlrev_b32_e32 v105, 2, v83
	v_cndmask_b32_e64 v83, v81, v73, s[2:3]
	v_cndmask_b32_e64 v84, v79, v71, s[2:3]
	v_cndmask_b32_e64 v71, v71, v79, s[2:3]
	v_cndmask_b32_e64 v79, v78, v70, s[2:3]
	v_add_f32_e32 v74, v74, v90
	s_waitcnt lgkmcnt(0)
	v_add_f32_e32 v82, v82, v86
	v_cndmask_b32_e64 v73, v73, v81, s[2:3]
	ds_bpermute_b32 v81, v105, v83
	v_cndmask_b32_e64 v83, v80, v72, s[2:3]
	v_cndmask_b32_e64 v72, v72, v80, s[2:3]
	v_cndmask_b32_e64 v70, v70, v78, s[2:3]
	ds_bpermute_b32 v78, v105, v79
	v_cndmask_b32_e64 v79, v77, v69, s[2:3]
	v_cndmask_b32_e64 v80, v76, v68, s[2:3]
	v_cndmask_b32_e64 v68, v68, v76, s[2:3]
	v_cndmask_b32_e64 v76, v75, v67, s[2:3]
	ds_bpermute_b32 v83, v105, v83
	ds_bpermute_b32 v79, v105, v79
	ds_bpermute_b32 v80, v105, v80
	v_cndmask_b32_e64 v67, v67, v75, s[2:3]
	ds_bpermute_b32 v75, v105, v76
	v_cndmask_b32_e64 v76, v74, v82, s[2:3]
	ds_bpermute_b32 v84, v105, v84
	ds_bpermute_b32 v76, v105, v76
	v_cndmask_b32_e64 v69, v69, v77, s[2:3]
	v_xor_b32_e32 v77, 4, v180
	v_and_b32_e32 v100, 4, v172
	v_cmp_lt_i32_e64 s[0:1], v77, v108
	s_waitcnt lgkmcnt(7)
	v_add_f32_e32 v73, v73, v81
	s_waitcnt lgkmcnt(5)
	v_add_f32_e32 v72, v72, v83
	s_waitcnt lgkmcnt(4)
	v_add_f32_e32 v69, v69, v79
	s_waitcnt lgkmcnt(3)
	v_add_f32_e32 v68, v68, v80
	v_cndmask_b32_e64 v77, v180, v77, s[0:1]
	v_cmp_eq_u32_e64 s[4:5], 0, v100
	v_cndmask_b32_e64 v74, v82, v74, s[2:3]
	s_waitcnt lgkmcnt(1)
	v_add_f32_e32 v71, v71, v84
	v_add_f32_e32 v70, v70, v78
	v_lshlrev_b32_e32 v106, 2, v77
	v_cndmask_b32_e64 v77, v73, v69, s[4:5]
	v_add_f32_e32 v67, v67, v75
	s_waitcnt lgkmcnt(0)
	v_add_f32_e32 v74, v74, v76
	v_cndmask_b32_e64 v69, v69, v73, s[4:5]
	v_cndmask_b32_e64 v73, v72, v68, s[4:5]
	v_cndmask_b32_e64 v68, v68, v72, s[4:5]
	ds_bpermute_b32 v72, v106, v73
	v_cndmask_b32_e64 v73, v71, v67, s[4:5]
	v_cndmask_b32_e64 v75, v70, v74, s[4:5]
	ds_bpermute_b32 v77, v106, v77
	ds_bpermute_b32 v73, v106, v73
	ds_bpermute_b32 v75, v106, v75
	v_cndmask_b32_e64 v67, v67, v71, s[4:5]
	v_xor_b32_e32 v71, 2, v180
	v_and_b32_e32 v101, 2, v172
	v_cndmask_b32_e64 v70, v74, v70, s[4:5]
	v_cmp_lt_i32_e64 s[0:1], v71, v108
	s_waitcnt lgkmcnt(2)
	v_add_f32_e32 v69, v69, v77
	v_add_f32_e32 v68, v68, v72
	s_waitcnt lgkmcnt(1)
	v_add_f32_e32 v67, v67, v73
	s_waitcnt lgkmcnt(0)
	v_add_f32_e32 v70, v70, v75
	v_cndmask_b32_e64 v71, v180, v71, s[0:1]
	v_cmp_eq_u32_e64 s[6:7], 0, v101
	v_lshlrev_b32_e32 v107, 2, v71
	v_and_b32_e32 v102, 1, v172
	v_cndmask_b32_e64 v71, v69, v67, s[6:7]
	v_cndmask_b32_e64 v72, v68, v70, s[6:7]
	ds_bpermute_b32 v71, v107, v71
	ds_bpermute_b32 v72, v107, v72
	v_cndmask_b32_e64 v67, v67, v69, s[6:7]
	v_xor_b32_e32 v69, 1, v180
	s_add_u32 s10, s70, s8
	v_cndmask_b32_e64 v68, v70, v68, s[6:7]
	v_cmp_lt_i32_e64 s[0:1], v69, v108
	s_addc_u32 s11, s71, s9
	s_waitcnt lgkmcnt(1)
	v_add_f32_e32 v67, v67, v71
	s_waitcnt lgkmcnt(0)
	v_add_f32_e32 v70, v68, v72
	v_cmp_eq_u32_e64 s[8:9], 0, v102
	v_cndmask_b32_e64 v69, v180, v69, s[0:1]
	v_lshlrev_b32_e32 v108, 2, v69
	v_cndmask_b32_e64 v68, v67, v70, s[8:9]
	ds_bpermute_b32 v71, v108, v68
	v_or3_b32 v66, v66, v173, v174
	v_lshlrev_b32_e32 v0, 2, v0
	v_lshl_add_u64 v[68:69], s[10:11], 0, v[0:1]
	v_cndmask_b32_e64 v0, v70, v67, s[8:9]
	v_ashrrev_i32_e32 v67, 31, v66
	s_waitcnt lgkmcnt(0)
	v_add_f32_e32 v0, v0, v71
	v_lshlrev_b64 v[70:71], 6, v[66:67]
	v_lshl_add_u64 v[70:71], v[68:69], 0, v[70:71]
	v_or_b32_e32 v100, 64, v136
	global_store_dword v[70:71], v0, off
	s_cmp_lg_u32 s32, 0
	s_cbranch_scc0 .Lrt0_c
	s_branch .LBB0_596
.Lrt0_c:
	v_min_i32_e32 v0, 0x403f, v100
	v_mul_hi_i32 v67, v0, s30
	v_lshrrev_b32_e32 v70, 31, v67
	v_ashrrev_i32_e32 v67, 11, v67
	v_add_u32_e32 v67, v67, v70
	v_mad_i32_i24 v0, v67, s31, v0
	v_cmp_lt_i32_e64 s[0:1], 15, v0
	s_and_saveexec_b64 s[10:11], s[0:1]
	s_xor_b64 s[0:1], exec, s[10:11]
	v_lshlrev_b32_e32 v67, 12, v67
	v_add3_u32 v70, v67, v0, -16
	v_ashrrev_i32_e32 v71, 31, v70
	v_lshlrev_b64 v[70:71], 12, v[70:71]
	v_lshl_add_u64 v[70:71], s[56:57], 0, v[70:71]
	s_andn2_saveexec_b64 s[0:1], s[0:1]
	v_lshlrev_b32_e32 v70, 10, v0
	v_ashrrev_i32_e32 v71, 31, v70
	v_lshl_add_u64 v[70:71], v[70:71], 2, s[58:59]
	s_or_b64 exec, exec, s[0:1]
	v_lshl_add_u64 v[70:71], v[130:131], 2, v[70:71]
	global_load_dword v0, v[70:71], off
	global_load_dword v67, v[70:71], off offset:128
	v_or_b32_e32 v98, 0x41, v136
	v_min_i32_e32 v70, 0x403f, v98
	v_mul_hi_i32 v71, v70, s30
	v_lshrrev_b32_e32 v72, 31, v71
	v_ashrrev_i32_e32 v71, 11, v71
	v_add_u32_e32 v73, v71, v72
	v_mad_i32_i24 v72, v73, s31, v70
	v_cmp_lt_i32_e64 s[0:1], 15, v72
	s_and_saveexec_b64 s[10:11], s[0:1]
	s_xor_b64 s[0:1], exec, s[10:11]
	v_lshlrev_b32_e32 v70, 12, v73
	v_add3_u32 v70, v70, v72, -16
	v_ashrrev_i32_e32 v71, 31, v70
	v_lshlrev_b64 v[70:71], 12, v[70:71]
	v_lshl_add_u64 v[70:71], s[56:57], 0, v[70:71]
	s_andn2_saveexec_b64 s[0:1], s[0:1]
	v_lshlrev_b32_e32 v70, 10, v72
	v_ashrrev_i32_e32 v71, 31, v70
	v_lshl_add_u64 v[70:71], v[70:71], 2, s[58:59]
	s_or_b64 exec, exec, s[0:1]
	v_lshl_add_u64 v[70:71], v[130:131], 2, v[70:71]
	global_load_dword v109, v[70:71], off
	global_load_dword v110, v[70:71], off offset:128
	v_or_b32_e32 v96, 0x42, v136
	v_min_i32_e32 v70, 0x403f, v96
	v_mul_hi_i32 v71, v70, s30
	v_lshrrev_b32_e32 v72, 31, v71
	v_ashrrev_i32_e32 v71, 11, v71
	v_add_u32_e32 v73, v71, v72
	v_mad_i32_i24 v72, v73, s31, v70
	v_cmp_lt_i32_e64 s[0:1], 15, v72
	s_and_saveexec_b64 s[10:11], s[0:1]
	s_xor_b64 s[0:1], exec, s[10:11]
	v_lshlrev_b32_e32 v70, 12, v73
	v_add3_u32 v70, v70, v72, -16
	v_ashrrev_i32_e32 v71, 31, v70
	v_lshlrev_b64 v[70:71], 12, v[70:71]
	v_lshl_add_u64 v[70:71], s[56:57], 0, v[70:71]
	s_andn2_saveexec_b64 s[0:1], s[0:1]
	v_lshlrev_b32_e32 v70, 10, v72
	v_ashrrev_i32_e32 v71, 31, v70
	v_lshl_add_u64 v[70:71], v[70:71], 2, s[58:59]
	s_or_b64 exec, exec, s[0:1]
	v_lshl_add_u64 v[70:71], v[130:131], 2, v[70:71]
	global_load_dword v111, v[70:71], off
	global_load_dword v112, v[70:71], off offset:128
	v_or_b32_e32 v94, 0x43, v136
	v_min_i32_e32 v70, 0x403f, v94
	v_mul_hi_i32 v71, v70, s30
	v_lshrrev_b32_e32 v72, 31, v71
	v_ashrrev_i32_e32 v71, 11, v71
	v_add_u32_e32 v73, v71, v72
	v_mad_i32_i24 v72, v73, s31, v70
	v_cmp_lt_i32_e64 s[0:1], 15, v72
	s_and_saveexec_b64 s[10:11], s[0:1]
	s_xor_b64 s[0:1], exec, s[10:11]
	v_lshlrev_b32_e32 v70, 12, v73
	v_add3_u32 v70, v70, v72, -16
	v_ashrrev_i32_e32 v71, 31, v70
	v_lshlrev_b64 v[70:71], 12, v[70:71]
	v_lshl_add_u64 v[70:71], s[56:57], 0, v[70:71]
	s_andn2_saveexec_b64 s[0:1], s[0:1]
	v_lshlrev_b32_e32 v70, 10, v72
	v_ashrrev_i32_e32 v71, 31, v70
	v_lshl_add_u64 v[70:71], v[70:71], 2, s[58:59]
	s_or_b64 exec, exec, s[0:1]
	v_lshl_add_u64 v[70:71], v[130:131], 2, v[70:71]
	global_load_dword v113, v[70:71], off
	global_load_dword v114, v[70:71], off offset:128
	v_or_b32_e32 v92, 0x48, v136
	v_min_i32_e32 v70, 0x403f, v92
	v_mul_hi_i32 v71, v70, s30
	v_lshrrev_b32_e32 v72, 31, v71
	v_ashrrev_i32_e32 v71, 11, v71
	v_add_u32_e32 v73, v71, v72
	v_mad_i32_i24 v72, v73, s31, v70
	v_cmp_lt_i32_e64 s[0:1], 15, v72
	s_and_saveexec_b64 s[10:11], s[0:1]
	s_xor_b64 s[0:1], exec, s[10:11]
	v_lshlrev_b32_e32 v70, 12, v73
	v_add3_u32 v70, v70, v72, -16
	v_ashrrev_i32_e32 v71, 31, v70
	v_lshlrev_b64 v[70:71], 12, v[70:71]
	v_lshl_add_u64 v[70:71], s[56:57], 0, v[70:71]
	s_andn2_saveexec_b64 s[0:1], s[0:1]
	v_lshlrev_b32_e32 v70, 10, v72
	v_ashrrev_i32_e32 v71, 31, v70
	v_lshl_add_u64 v[70:71], v[70:71], 2, s[58:59]
	s_or_b64 exec, exec, s[0:1]
	v_lshl_add_u64 v[70:71], v[130:131], 2, v[70:71]
	global_load_dword v115, v[70:71], off
	global_load_dword v116, v[70:71], off offset:128
	v_or_b32_e32 v90, 0x49, v136
	v_min_i32_e32 v70, 0x403f, v90
	v_mul_hi_i32 v71, v70, s30
	v_lshrrev_b32_e32 v72, 31, v71
	v_ashrrev_i32_e32 v71, 11, v71
	v_add_u32_e32 v73, v71, v72
	v_mad_i32_i24 v72, v73, s31, v70
	v_cmp_lt_i32_e64 s[0:1], 15, v72
	s_and_saveexec_b64 s[10:11], s[0:1]
	s_xor_b64 s[0:1], exec, s[10:11]
	v_lshlrev_b32_e32 v70, 12, v73
	v_add3_u32 v70, v70, v72, -16
	v_ashrrev_i32_e32 v71, 31, v70
	v_lshlrev_b64 v[70:71], 12, v[70:71]
	v_lshl_add_u64 v[70:71], s[56:57], 0, v[70:71]
	s_andn2_saveexec_b64 s[0:1], s[0:1]
	v_lshlrev_b32_e32 v70, 10, v72
	v_ashrrev_i32_e32 v71, 31, v70
	v_lshl_add_u64 v[70:71], v[70:71], 2, s[58:59]
	s_or_b64 exec, exec, s[0:1]
	v_lshl_add_u64 v[70:71], v[130:131], 2, v[70:71]
	global_load_dword v117, v[70:71], off
	global_load_dword v118, v[70:71], off offset:128
	v_or_b32_e32 v88, 0x4a, v136
	v_min_i32_e32 v70, 0x403f, v88
	v_mul_hi_i32 v71, v70, s30
	v_lshrrev_b32_e32 v72, 31, v71
	v_ashrrev_i32_e32 v71, 11, v71
	v_add_u32_e32 v73, v71, v72
	v_mad_i32_i24 v72, v73, s31, v70
	v_cmp_lt_i32_e64 s[0:1], 15, v72
	s_and_saveexec_b64 s[10:11], s[0:1]
	s_xor_b64 s[0:1], exec, s[10:11]
	v_lshlrev_b32_e32 v70, 12, v73
	v_add3_u32 v70, v70, v72, -16
	v_ashrrev_i32_e32 v71, 31, v70
	v_lshlrev_b64 v[70:71], 12, v[70:71]
	v_lshl_add_u64 v[70:71], s[56:57], 0, v[70:71]
	s_andn2_saveexec_b64 s[0:1], s[0:1]
	v_lshlrev_b32_e32 v70, 10, v72
	v_ashrrev_i32_e32 v71, 31, v70
	v_lshl_add_u64 v[70:71], v[70:71], 2, s[58:59]
	s_or_b64 exec, exec, s[0:1]
	v_lshl_add_u64 v[70:71], v[130:131], 2, v[70:71]
	global_load_dword v119, v[70:71], off
	global_load_dword v120, v[70:71], off offset:128
	v_or_b32_e32 v86, 0x4b, v136
	v_min_i32_e32 v70, 0x403f, v86
	v_mul_hi_i32 v71, v70, s30
	v_lshrrev_b32_e32 v72, 31, v71
	v_ashrrev_i32_e32 v71, 11, v71
	v_add_u32_e32 v73, v71, v72
	v_mad_i32_i24 v72, v73, s31, v70
	v_cmp_lt_i32_e64 s[0:1], 15, v72
	s_and_saveexec_b64 s[10:11], s[0:1]
	s_xor_b64 s[0:1], exec, s[10:11]
	v_lshlrev_b32_e32 v70, 12, v73
	v_add3_u32 v70, v70, v72, -16
	v_ashrrev_i32_e32 v71, 31, v70
	v_lshlrev_b64 v[70:71], 12, v[70:71]
	v_lshl_add_u64 v[70:71], s[56:57], 0, v[70:71]
	s_andn2_saveexec_b64 s[0:1], s[0:1]
	v_lshlrev_b32_e32 v70, 10, v72
	v_ashrrev_i32_e32 v71, 31, v70
	v_lshl_add_u64 v[70:71], v[70:71], 2, s[58:59]
	s_or_b64 exec, exec, s[0:1]
	v_lshl_add_u64 v[70:71], v[130:131], 2, v[70:71]
	global_load_dword v121, v[70:71], off
	global_load_dword v122, v[70:71], off offset:128
	v_or_b32_e32 v84, 0x50, v136
	v_min_i32_e32 v70, 0x403f, v84
	v_mul_hi_i32 v71, v70, s30
	v_lshrrev_b32_e32 v72, 31, v71
	v_ashrrev_i32_e32 v71, 11, v71
	v_add_u32_e32 v73, v71, v72
	v_mad_i32_i24 v72, v73, s31, v70
	v_cmp_lt_i32_e64 s[0:1], 15, v72
	s_and_saveexec_b64 s[10:11], s[0:1]
	s_xor_b64 s[0:1], exec, s[10:11]
	v_lshlrev_b32_e32 v70, 12, v73
	v_add3_u32 v70, v70, v72, -16
	v_ashrrev_i32_e32 v71, 31, v70
	v_lshlrev_b64 v[70:71], 12, v[70:71]
	v_lshl_add_u64 v[70:71], s[56:57], 0, v[70:71]
	s_andn2_saveexec_b64 s[0:1], s[0:1]
	v_lshlrev_b32_e32 v70, 10, v72
	v_ashrrev_i32_e32 v71, 31, v70
	v_lshl_add_u64 v[70:71], v[70:71], 2, s[58:59]
	s_or_b64 exec, exec, s[0:1]
	v_lshl_add_u64 v[70:71], v[130:131], 2, v[70:71]
	global_load_dword v123, v[70:71], off
	global_load_dword v124, v[70:71], off offset:128
	v_or_b32_e32 v82, 0x51, v136
	v_min_i32_e32 v70, 0x403f, v82
	v_mul_hi_i32 v71, v70, s30
	v_lshrrev_b32_e32 v72, 31, v71
	v_ashrrev_i32_e32 v71, 11, v71
	v_add_u32_e32 v73, v71, v72
	v_mad_i32_i24 v72, v73, s31, v70
	v_cmp_lt_i32_e64 s[0:1], 15, v72
	s_and_saveexec_b64 s[10:11], s[0:1]
	s_xor_b64 s[0:1], exec, s[10:11]
	v_lshlrev_b32_e32 v70, 12, v73
	v_add3_u32 v70, v70, v72, -16
	v_ashrrev_i32_e32 v71, 31, v70
	v_lshlrev_b64 v[70:71], 12, v[70:71]
	v_lshl_add_u64 v[70:71], s[56:57], 0, v[70:71]
	s_andn2_saveexec_b64 s[0:1], s[0:1]
	v_lshlrev_b32_e32 v70, 10, v72
	v_ashrrev_i32_e32 v71, 31, v70
	v_lshl_add_u64 v[70:71], v[70:71], 2, s[58:59]
	s_or_b64 exec, exec, s[0:1]
	v_lshl_add_u64 v[70:71], v[130:131], 2, v[70:71]
	global_load_dword v125, v[70:71], off
	global_load_dword v126, v[70:71], off offset:128
	v_or_b32_e32 v80, 0x52, v136
	v_min_i32_e32 v70, 0x403f, v80
	v_mul_hi_i32 v71, v70, s30
	v_lshrrev_b32_e32 v72, 31, v71
	v_ashrrev_i32_e32 v71, 11, v71
	v_add_u32_e32 v73, v71, v72
	v_mad_i32_i24 v72, v73, s31, v70
	v_cmp_lt_i32_e64 s[0:1], 15, v72
	s_and_saveexec_b64 s[10:11], s[0:1]
	s_xor_b64 s[0:1], exec, s[10:11]
	v_lshlrev_b32_e32 v70, 12, v73
	v_add3_u32 v70, v70, v72, -16
	v_ashrrev_i32_e32 v71, 31, v70
	v_lshlrev_b64 v[70:71], 12, v[70:71]
	v_lshl_add_u64 v[70:71], s[56:57], 0, v[70:71]
	s_andn2_saveexec_b64 s[0:1], s[0:1]
	v_lshlrev_b32_e32 v70, 10, v72
	v_ashrrev_i32_e32 v71, 31, v70
	v_lshl_add_u64 v[70:71], v[70:71], 2, s[58:59]
	s_or_b64 exec, exec, s[0:1]
	v_lshl_add_u64 v[70:71], v[130:131], 2, v[70:71]
	global_load_dword v127, v[70:71], off
	global_load_dword v128, v[70:71], off offset:128
	v_or_b32_e32 v78, 0x53, v136
	v_min_i32_e32 v70, 0x403f, v78
	v_mul_hi_i32 v71, v70, s30
	v_lshrrev_b32_e32 v72, 31, v71
	v_ashrrev_i32_e32 v71, 11, v71
	v_add_u32_e32 v73, v71, v72
	v_mad_i32_i24 v72, v73, s31, v70
	v_cmp_lt_i32_e64 s[0:1], 15, v72
	s_and_saveexec_b64 s[10:11], s[0:1]
	s_xor_b64 s[0:1], exec, s[10:11]
	v_lshlrev_b32_e32 v70, 12, v73
	v_add3_u32 v70, v70, v72, -16
	v_ashrrev_i32_e32 v71, 31, v70
	v_lshlrev_b64 v[70:71], 12, v[70:71]
	v_lshl_add_u64 v[70:71], s[56:57], 0, v[70:71]
	s_andn2_saveexec_b64 s[0:1], s[0:1]
	v_lshlrev_b32_e32 v70, 10, v72
	v_ashrrev_i32_e32 v71, 31, v70
	v_lshl_add_u64 v[70:71], v[70:71], 2, s[58:59]
	s_or_b64 exec, exec, s[0:1]
	v_lshl_add_u64 v[70:71], v[130:131], 2, v[70:71]
	global_load_dword v129, v[70:71], off
	global_load_dword v137, v[70:71], off offset:128
	v_or_b32_e32 v76, 0x58, v136
	v_min_i32_e32 v70, 0x403f, v76
	v_mul_hi_i32 v71, v70, s30
	v_lshrrev_b32_e32 v72, 31, v71
	v_ashrrev_i32_e32 v71, 11, v71
	v_add_u32_e32 v73, v71, v72
	v_mad_i32_i24 v72, v73, s31, v70
	v_cmp_lt_i32_e64 s[0:1], 15, v72
	s_and_saveexec_b64 s[10:11], s[0:1]
	s_xor_b64 s[0:1], exec, s[10:11]
	v_lshlrev_b32_e32 v70, 12, v73
	v_add3_u32 v70, v70, v72, -16
	v_ashrrev_i32_e32 v71, 31, v70
	v_lshlrev_b64 v[70:71], 12, v[70:71]
	v_lshl_add_u64 v[70:71], s[56:57], 0, v[70:71]
	s_andn2_saveexec_b64 s[0:1], s[0:1]
	v_lshlrev_b32_e32 v70, 10, v72
	v_ashrrev_i32_e32 v71, 31, v70
	v_lshl_add_u64 v[70:71], v[70:71], 2, s[58:59]
	s_or_b64 exec, exec, s[0:1]
	v_lshl_add_u64 v[70:71], v[130:131], 2, v[70:71]
	global_load_dword v138, v[70:71], off
	global_load_dword v139, v[70:71], off offset:128
	v_or_b32_e32 v74, 0x59, v136
	v_min_i32_e32 v70, 0x403f, v74
	v_mul_hi_i32 v71, v70, s30
	v_lshrrev_b32_e32 v72, 31, v71
	v_ashrrev_i32_e32 v71, 11, v71
	v_add_u32_e32 v73, v71, v72
	v_mad_i32_i24 v72, v73, s31, v70
	v_cmp_lt_i32_e64 s[0:1], 15, v72
	s_and_saveexec_b64 s[10:11], s[0:1]
	s_xor_b64 s[0:1], exec, s[10:11]
	v_lshlrev_b32_e32 v70, 12, v73
	v_add3_u32 v70, v70, v72, -16
	v_ashrrev_i32_e32 v71, 31, v70
	v_lshlrev_b64 v[70:71], 12, v[70:71]
	v_lshl_add_u64 v[70:71], s[56:57], 0, v[70:71]
	s_andn2_saveexec_b64 s[0:1], s[0:1]
	v_lshlrev_b32_e32 v70, 10, v72
	v_ashrrev_i32_e32 v71, 31, v70
	v_lshl_add_u64 v[70:71], v[70:71], 2, s[58:59]
	s_or_b64 exec, exec, s[0:1]
	v_lshl_add_u64 v[70:71], v[130:131], 2, v[70:71]
	global_load_dword v140, v[70:71], off
	global_load_dword v141, v[70:71], off offset:128
	v_or_b32_e32 v72, 0x5a, v136
	v_min_i32_e32 v70, 0x403f, v72
	v_mul_hi_i32 v71, v70, s30
	v_lshrrev_b32_e32 v73, 31, v71
	v_ashrrev_i32_e32 v71, 11, v71
	v_add_u32_e32 v75, v71, v73
	v_mad_i32_i24 v73, v75, s31, v70
	v_cmp_lt_i32_e64 s[0:1], 15, v73
	s_and_saveexec_b64 s[10:11], s[0:1]
	s_xor_b64 s[0:1], exec, s[10:11]
	v_lshlrev_b32_e32 v70, 12, v75
	v_add3_u32 v70, v70, v73, -16
	v_ashrrev_i32_e32 v71, 31, v70
	v_lshlrev_b64 v[70:71], 12, v[70:71]
	v_lshl_add_u64 v[70:71], s[56:57], 0, v[70:71]
	s_andn2_saveexec_b64 s[0:1], s[0:1]
	v_lshlrev_b32_e32 v70, 10, v73
	v_ashrrev_i32_e32 v71, 31, v70
	v_lshl_add_u64 v[70:71], v[70:71], 2, s[58:59]
	s_or_b64 exec, exec, s[0:1]
	v_lshl_add_u64 v[70:71], v[130:131], 2, v[70:71]
	global_load_dword v142, v[70:71], off
	global_load_dword v143, v[70:71], off offset:128
	v_or_b32_e32 v70, 0x5b, v136
	v_min_i32_e32 v71, 0x403f, v70
	v_mul_hi_i32 v73, v71, s30
	v_lshrrev_b32_e32 v75, 31, v73
	v_ashrrev_i32_e32 v73, 11, v73
	v_add_u32_e32 v73, v73, v75
	v_mad_i32_i24 v71, v73, s31, v71
	v_cmp_lt_i32_e64 s[0:1], 15, v71
	s_and_saveexec_b64 s[10:11], s[0:1]
	s_xor_b64 s[0:1], exec, s[10:11]
	v_lshlrev_b32_e32 v73, 12, v73
	v_add3_u32 v102, v73, v71, -16
	v_ashrrev_i32_e32 v103, 31, v102
	v_lshlrev_b64 v[102:103], 12, v[102:103]
	v_lshl_add_u64 v[102:103], s[56:57], 0, v[102:103]
	s_andn2_saveexec_b64 s[0:1], s[0:1]
	v_lshlrev_b32_e32 v102, 10, v71
	v_ashrrev_i32_e32 v103, 31, v102
	v_lshl_add_u64 v[102:103], v[102:103], 2, s[58:59]
	s_or_b64 exec, exec, s[0:1]
	v_lshl_add_u64 v[102:103], v[130:131], 2, v[102:103]
	global_load_dword v144, v[102:103], off
	global_load_dword v145, v[102:103], off offset:128
	v_cmp_gt_i32_e64 s[10:11], s34, v100
	s_nop 1
	v_cndmask_b32_e64 v73, v179, v100, s[10:11]
	v_mul_hi_i32 v71, v73, s30
	v_lshrrev_b32_e32 v75, 31, v71
	v_ashrrev_i32_e32 v71, 11, v71
	v_add_u32_e32 v71, v71, v75
	v_mad_i32_i24 v73, v71, s31, v73
	v_cmp_lt_i32_e64 s[0:1], 15, v73
	s_and_saveexec_b64 s[36:37], s[0:1]
	s_xor_b64 s[0:1], exec, s[36:37]
	v_lshlrev_b32_e32 v71, 12, v71
	v_add3_u32 v102, v71, v73, -16
	v_ashrrev_i32_e32 v103, 31, v102
	v_lshlrev_b64 v[102:103], 12, v[102:103]
	v_lshl_add_u64 v[102:103], s[88:89], 0, v[102:103]
	s_andn2_saveexec_b64 s[0:1], s[0:1]
	v_lshlrev_b32_e32 v71, 14, v71
	v_lshl_add_u32 v102, v73, 10, v71
	v_ashrrev_i32_e32 v103, 31, v102
	v_lshl_add_u64 v[102:103], v[102:103], 2, s[12:13]
	s_or_b64 exec, exec, s[0:1]
	v_ashrrev_i32_e32 v101, 31, v100
	v_lshlrev_b64 v[100:101], 11, v[100:101]
	v_lshl_add_u64 v[100:101], s[62:63], 0, v[100:101]
	s_waitcnt vmcnt(31)
	v_fmac_f32_e32 v0, 0.5, v50
	v_lshl_add_u64 v[100:101], v[130:131], 1, v[100:101]
	v_lshl_add_u64 v[102:103], v[102:103], 0, v[134:135]
	s_and_saveexec_b64 s[0:1], s[10:11]
	s_cbranch_execz .LBB0_1113
	global_store_dword v[102:103], v0, off
	v_mul_f32_e32 v50, v0, v242
	v_cvt_pk_bf16_f32 v50, v50, s0
	global_store_short v[100:101], v50, off

.LBB0_3640:
	s_and_b64 vcc, exec, s[10:11]
	s_cbranch_vccz .LBB0_3578
	s_cmpk_ge_i32 s6, 0x4000
	s_cselect_b32 s32, 1, 0
	s_cbranch_scc0 .Lrt1_f
	v_readfirstlane_b32 s98, v208
	s_bitcmp1_b32 s98, 8
	s_cbranch_scc0 .Lrt1_f
	s_waitcnt vmcnt(0)
	s_branch .LBB0_3578
.Lrt1_f:
	v_mov_b32_e32 v172, v208
	s_nop 0
	v_ashrrev_i32_e32 v0, 1, v172
	v_and_b32_e32 v0, 0xffffff80, v0
	s_waitcnt vmcnt(7)
	v_lshrrev_b32_e32 v130, 3, v172
	v_and_b32_e32 v173, 4, v130
	v_add_u32_e32 v174, s6, v0
	s_waitcnt vmcnt(6)
	v_or_b32_e32 v136, v174, v173
	v_min_i32_e32 v130, 0x403f, v136
	v_mul_hi_i32 v0, v130, s83
	v_lshrrev_b32_e32 v131, 31, v0
	v_ashrrev_i32_e32 v0, 11, v0
	v_add_u32_e32 v0, v0, v131
	v_mad_i32_i24 v130, v0, s84, v130
	v_cmp_lt_i32_e32 vcc, 15, v130
	s_and_saveexec_b64 s[2:3], vcc
	s_xor_b64 s[2:3], exec, s[2:3]
	v_lshlrev_b32_e32 v0, 12, v0
	v_add3_u32 v130, v0, v130, -16
	v_ashrrev_i32_e32 v131, 31, v130
	v_lshlrev_b64 v[130:131], 12, v[130:131]
	v_lshl_add_u64 v[132:133], s[88:89], 0, v[130:131]
	s_andn2_saveexec_b64 s[2:3], s[2:3]
	v_lshlrev_b32_e32 v0, 14, v0
	v_lshl_add_u32 v130, v130, 10, v0
	v_ashrrev_i32_e32 v131, 31, v130
	v_lshl_add_u64 v[132:133], v[130:131], 2, s[16:17]
	s_or_b64 exec, exec, s[2:3]
	v_bfe_u32 v0, v172, 6, 2
	v_and_b32_e32 v175, 31, v172
	v_lshlrev_b32_e32 v130, 6, v0
	v_or3_b32 v130, v130, s0, v175
	v_ashrrev_i32_e32 v131, 31, v130
	v_lshl_add_u64 v[132:133], v[130:131], 2, v[132:133]
	global_load_dword v134, v[132:133], off
	global_load_dword v167, v[132:133], off offset:128
	v_or_b32_e32 v166, 1, v136
	v_min_i32_e32 v132, 0x403f, v166
	v_mul_hi_i32 v133, v132, s83
	v_lshrrev_b32_e32 v135, 31, v133
	v_ashrrev_i32_e32 v133, 11, v133
	v_add_u32_e32 v135, v133, v135
	v_mad_i32_i24 v137, v135, s84, v132
	v_cmp_lt_i32_e32 vcc, 15, v137
	s_and_saveexec_b64 s[0:1], vcc
	s_xor_b64 s[0:1], exec, s[0:1]
	v_lshlrev_b32_e32 v132, 12, v135
	v_add3_u32 v132, v132, v137, -16
	v_ashrrev_i32_e32 v133, 31, v132
	v_lshlrev_b64 v[132:133], 12, v[132:133]
	v_lshl_add_u64 v[132:133], s[88:89], 0, v[132:133]
	s_andn2_saveexec_b64 s[0:1], s[0:1]
	v_lshlrev_b32_e32 v132, 14, v135
	v_lshl_add_u32 v132, v137, 10, v132
	v_ashrrev_i32_e32 v133, 31, v132
	v_lshl_add_u64 v[132:133], v[132:133], 2, s[16:17]
	s_or_b64 exec, exec, s[0:1]
	v_lshl_add_u64 v[132:133], v[130:131], 2, v[132:133]
	global_load_dword v194, v[132:133], off
	global_load_dword v165, v[132:133], off offset:128
	v_or_b32_e32 v164, 2, v136
	v_min_i32_e32 v132, 0x403f, v164
	v_mul_hi_i32 v133, v132, s83
	v_lshrrev_b32_e32 v135, 31, v133
	v_ashrrev_i32_e32 v133, 11, v133
	v_add_u32_e32 v135, v133, v135
	v_mad_i32_i24 v137, v135, s84, v132
	v_cmp_lt_i32_e32 vcc, 15, v137
	s_and_saveexec_b64 s[0:1], vcc
	s_xor_b64 s[0:1], exec, s[0:1]
	v_lshlrev_b32_e32 v132, 12, v135
	v_add3_u32 v132, v132, v137, -16
	v_ashrrev_i32_e32 v133, 31, v132
	v_lshlrev_b64 v[132:133], 12, v[132:133]
	v_lshl_add_u64 v[132:133], s[88:89], 0, v[132:133]
	s_andn2_saveexec_b64 s[0:1], s[0:1]
	v_lshlrev_b32_e32 v132, 14, v135
	v_lshl_add_u32 v132, v137, 10, v132
	v_ashrrev_i32_e32 v133, 31, v132
	v_lshl_add_u64 v[132:133], v[132:133], 2, s[16:17]
	s_or_b64 exec, exec, s[0:1]
	v_lshl_add_u64 v[132:133], v[130:131], 2, v[132:133]
	global_load_dword v193, v[132:133], off
	global_load_dword v163, v[132:133], off offset:128
	v_or_b32_e32 v162, 3, v136
	v_min_i32_e32 v132, 0x403f, v162
	v_mul_hi_i32 v133, v132, s83
	v_lshrrev_b32_e32 v135, 31, v133
	v_ashrrev_i32_e32 v133, 11, v133
	v_add_u32_e32 v135, v133, v135
	v_mad_i32_i24 v137, v135, s84, v132
	v_cmp_lt_i32_e32 vcc, 15, v137
	s_and_saveexec_b64 s[0:1], vcc
	s_xor_b64 s[0:1], exec, s[0:1]
	v_lshlrev_b32_e32 v132, 12, v135
	v_add3_u32 v132, v132, v137, -16
	v_ashrrev_i32_e32 v133, 31, v132
	v_lshlrev_b64 v[132:133], 12, v[132:133]
	v_lshl_add_u64 v[132:133], s[88:89], 0, v[132:133]
	s_andn2_saveexec_b64 s[0:1], s[0:1]
	v_lshlrev_b32_e32 v132, 14, v135
	v_lshl_add_u32 v132, v137, 10, v132
	v_ashrrev_i32_e32 v133, 31, v132
	v_lshl_add_u64 v[132:133], v[132:133], 2, s[16:17]
	s_or_b64 exec, exec, s[0:1]
	v_lshl_add_u64 v[132:133], v[130:131], 2, v[132:133]
	global_load_dword v192, v[132:133], off
	global_load_dword v161, v[132:133], off offset:128
	s_waitcnt vmcnt(13)
	v_or_b32_e32 v160, 8, v136
	v_min_i32_e32 v132, 0x403f, v160
	v_mul_hi_i32 v133, v132, s83
	v_lshrrev_b32_e32 v135, 31, v133
	v_ashrrev_i32_e32 v133, 11, v133
	v_add_u32_e32 v135, v133, v135
	v_mad_i32_i24 v137, v135, s84, v132
	v_cmp_lt_i32_e32 vcc, 15, v137
	s_and_saveexec_b64 s[0:1], vcc
	s_xor_b64 s[0:1], exec, s[0:1]
	v_lshlrev_b32_e32 v132, 12, v135
	v_add3_u32 v132, v132, v137, -16
	v_ashrrev_i32_e32 v133, 31, v132
	v_lshlrev_b64 v[132:133], 12, v[132:133]
	v_lshl_add_u64 v[132:133], s[88:89], 0, v[132:133]
	s_andn2_saveexec_b64 s[0:1], s[0:1]
	v_lshlrev_b32_e32 v132, 14, v135
	v_lshl_add_u32 v132, v137, 10, v132
	v_ashrrev_i32_e32 v133, 31, v132
	v_lshl_add_u64 v[132:133], v[132:133], 2, s[16:17]
	s_or_b64 exec, exec, s[0:1]
	v_lshl_add_u64 v[132:133], v[130:131], 2, v[132:133]
	global_load_dword v191, v[132:133], off
	global_load_dword v159, v[132:133], off offset:128
	v_or_b32_e32 v158, 9, v136
	v_min_i32_e32 v132, 0x403f, v158
	v_mul_hi_i32 v133, v132, s83
	v_lshrrev_b32_e32 v135, 31, v133
	v_ashrrev_i32_e32 v133, 11, v133
	v_add_u32_e32 v135, v133, v135
	v_mad_i32_i24 v137, v135, s84, v132
	v_cmp_lt_i32_e32 vcc, 15, v137
	s_and_saveexec_b64 s[0:1], vcc
	s_xor_b64 s[0:1], exec, s[0:1]
	v_lshlrev_b32_e32 v132, 12, v135
	v_add3_u32 v132, v132, v137, -16
	v_ashrrev_i32_e32 v133, 31, v132
	v_lshlrev_b64 v[132:133], 12, v[132:133]
	v_lshl_add_u64 v[132:133], s[88:89], 0, v[132:133]
	s_andn2_saveexec_b64 s[0:1], s[0:1]
	v_lshlrev_b32_e32 v132, 14, v135
	v_lshl_add_u32 v132, v137, 10, v132
	v_ashrrev_i32_e32 v133, 31, v132
	v_lshl_add_u64 v[132:133], v[132:133], 2, s[16:17]
	s_or_b64 exec, exec, s[0:1]
	v_lshl_add_u64 v[132:133], v[130:131], 2, v[132:133]
	global_load_dword v190, v[132:133], off
	global_load_dword v157, v[132:133], off offset:128
	s_waitcnt vmcnt(12)
	v_or_b32_e32 v156, 10, v136
	v_min_i32_e32 v132, 0x403f, v156
	v_mul_hi_i32 v133, v132, s83
	v_lshrrev_b32_e32 v135, 31, v133
	v_ashrrev_i32_e32 v133, 11, v133
	v_add_u32_e32 v135, v133, v135
	v_mad_i32_i24 v137, v135, s84, v132
	v_cmp_lt_i32_e32 vcc, 15, v137
	s_and_saveexec_b64 s[0:1], vcc
	s_xor_b64 s[0:1], exec, s[0:1]
	v_lshlrev_b32_e32 v132, 12, v135
	v_add3_u32 v132, v132, v137, -16
	v_ashrrev_i32_e32 v133, 31, v132
	v_lshlrev_b64 v[132:133], 12, v[132:133]
	v_lshl_add_u64 v[132:133], s[88:89], 0, v[132:133]
	s_andn2_saveexec_b64 s[0:1], s[0:1]
	v_lshlrev_b32_e32 v132, 14, v135
	v_lshl_add_u32 v132, v137, 10, v132
	v_ashrrev_i32_e32 v133, 31, v132
	v_lshl_add_u64 v[132:133], v[132:133], 2, s[16:17]
	s_or_b64 exec, exec, s[0:1]
	v_lshl_add_u64 v[132:133], v[130:131], 2, v[132:133]
	global_load_dword v189, v[132:133], off
	global_load_dword v155, v[132:133], off offset:128
	v_or_b32_e32 v154, 11, v136
	v_min_i32_e32 v132, 0x403f, v154
	v_mul_hi_i32 v133, v132, s83
	v_lshrrev_b32_e32 v135, 31, v133
	v_ashrrev_i32_e32 v133, 11, v133
	v_add_u32_e32 v135, v133, v135
	v_mad_i32_i24 v137, v135, s84, v132
	v_cmp_lt_i32_e32 vcc, 15, v137
	s_and_saveexec_b64 s[0:1], vcc
	s_xor_b64 s[0:1], exec, s[0:1]
	v_lshlrev_b32_e32 v132, 12, v135
	v_add3_u32 v132, v132, v137, -16
	v_ashrrev_i32_e32 v133, 31, v132
	v_lshlrev_b64 v[132:133], 12, v[132:133]
	v_lshl_add_u64 v[132:133], s[88:89], 0, v[132:133]
	s_andn2_saveexec_b64 s[0:1], s[0:1]
	v_lshlrev_b32_e32 v132, 14, v135
	v_lshl_add_u32 v132, v137, 10, v132
	v_ashrrev_i32_e32 v133, 31, v132
	v_lshl_add_u64 v[132:133], v[132:133], 2, s[16:17]
	s_or_b64 exec, exec, s[0:1]
	v_lshl_add_u64 v[132:133], v[130:131], 2, v[132:133]
	global_load_dword v188, v[132:133], off
	global_load_dword v153, v[132:133], off offset:128
	v_or_b32_e32 v152, 16, v136
	v_min_i32_e32 v132, 0x403f, v152
	v_mul_hi_i32 v133, v132, s83
	v_lshrrev_b32_e32 v135, 31, v133
	v_ashrrev_i32_e32 v133, 11, v133
	v_add_u32_e32 v135, v133, v135
	v_mad_i32_i24 v137, v135, s84, v132
	v_cmp_lt_i32_e32 vcc, 15, v137
	s_and_saveexec_b64 s[0:1], vcc
	s_xor_b64 s[0:1], exec, s[0:1]
	v_lshlrev_b32_e32 v132, 12, v135
	v_add3_u32 v132, v132, v137, -16
	v_ashrrev_i32_e32 v133, 31, v132
	v_lshlrev_b64 v[132:133], 12, v[132:133]
	v_lshl_add_u64 v[132:133], s[88:89], 0, v[132:133]
	s_andn2_saveexec_b64 s[0:1], s[0:1]
	v_lshlrev_b32_e32 v132, 14, v135
	v_lshl_add_u32 v132, v137, 10, v132
	v_ashrrev_i32_e32 v133, 31, v132
	v_lshl_add_u64 v[132:133], v[132:133], 2, s[16:17]
	s_or_b64 exec, exec, s[0:1]
	v_lshl_add_u64 v[132:133], v[130:131], 2, v[132:133]
	global_load_dword v187, v[132:133], off
	global_load_dword v151, v[132:133], off offset:128
	v_or_b32_e32 v150, 17, v136
	v_min_i32_e32 v132, 0x403f, v150
	v_mul_hi_i32 v133, v132, s83
	v_lshrrev_b32_e32 v135, 31, v133
	v_ashrrev_i32_e32 v133, 11, v133
	v_add_u32_e32 v135, v133, v135
	v_mad_i32_i24 v137, v135, s84, v132
	v_cmp_lt_i32_e32 vcc, 15, v137
	s_and_saveexec_b64 s[0:1], vcc
	s_xor_b64 s[0:1], exec, s[0:1]
	v_lshlrev_b32_e32 v132, 12, v135
	v_add3_u32 v132, v132, v137, -16
	v_ashrrev_i32_e32 v133, 31, v132
	v_lshlrev_b64 v[132:133], 12, v[132:133]
	v_lshl_add_u64 v[132:133], s[88:89], 0, v[132:133]
	s_andn2_saveexec_b64 s[0:1], s[0:1]
	v_lshlrev_b32_e32 v132, 14, v135
	v_lshl_add_u32 v132, v137, 10, v132
	v_ashrrev_i32_e32 v133, 31, v132
	v_lshl_add_u64 v[132:133], v[132:133], 2, s[16:17]
	s_or_b64 exec, exec, s[0:1]
	v_lshl_add_u64 v[132:133], v[130:131], 2, v[132:133]
	global_load_dword v186, v[132:133], off
	global_load_dword v149, v[132:133], off offset:128
	v_or_b32_e32 v148, 18, v136
	v_min_i32_e32 v132, 0x403f, v148
	v_mul_hi_i32 v133, v132, s83
	v_lshrrev_b32_e32 v135, 31, v133
	v_ashrrev_i32_e32 v133, 11, v133
	v_add_u32_e32 v135, v133, v135
	v_mad_i32_i24 v137, v135, s84, v132
	v_cmp_lt_i32_e32 vcc, 15, v137
	s_and_saveexec_b64 s[0:1], vcc
	s_xor_b64 s[0:1], exec, s[0:1]
	v_lshlrev_b32_e32 v132, 12, v135
	v_add3_u32 v132, v132, v137, -16
	v_ashrrev_i32_e32 v133, 31, v132
	v_lshlrev_b64 v[132:133], 12, v[132:133]
	v_lshl_add_u64 v[132:133], s[88:89], 0, v[132:133]
	s_andn2_saveexec_b64 s[0:1], s[0:1]
	v_lshlrev_b32_e32 v132, 14, v135
	v_lshl_add_u32 v132, v137, 10, v132
	v_ashrrev_i32_e32 v133, 31, v132
	v_lshl_add_u64 v[132:133], v[132:133], 2, s[16:17]
	s_or_b64 exec, exec, s[0:1]
	v_lshl_add_u64 v[132:133], v[130:131], 2, v[132:133]
	global_load_dword v185, v[132:133], off
	global_load_dword v147, v[132:133], off offset:128
	v_or_b32_e32 v146, 19, v136
	v_min_i32_e32 v132, 0x403f, v146
	v_mul_hi_i32 v133, v132, s83
	v_lshrrev_b32_e32 v135, 31, v133
	v_ashrrev_i32_e32 v133, 11, v133
	v_add_u32_e32 v135, v133, v135
	v_mad_i32_i24 v137, v135, s84, v132
	v_cmp_lt_i32_e32 vcc, 15, v137
	s_and_saveexec_b64 s[0:1], vcc
	s_xor_b64 s[0:1], exec, s[0:1]
	v_lshlrev_b32_e32 v132, 12, v135
	v_add3_u32 v132, v132, v137, -16
	v_ashrrev_i32_e32 v133, 31, v132
	v_lshlrev_b64 v[132:133], 12, v[132:133]
	v_lshl_add_u64 v[132:133], s[88:89], 0, v[132:133]
	s_andn2_saveexec_b64 s[0:1], s[0:1]
	v_lshlrev_b32_e32 v132, 14, v135
	v_lshl_add_u32 v132, v137, 10, v132
	v_ashrrev_i32_e32 v133, 31, v132
	v_lshl_add_u64 v[132:133], v[132:133], 2, s[16:17]
	s_or_b64 exec, exec, s[0:1]
	v_lshl_add_u64 v[132:133], v[130:131], 2, v[132:133]
	global_load_dword v184, v[132:133], off
	global_load_dword v145, v[132:133], off offset:128
	v_or_b32_e32 v144, 24, v136
	v_min_i32_e32 v132, 0x403f, v144
	v_mul_hi_i32 v133, v132, s83
	v_lshrrev_b32_e32 v135, 31, v133
	v_ashrrev_i32_e32 v133, 11, v133
	v_add_u32_e32 v135, v133, v135
	v_mad_i32_i24 v137, v135, s84, v132
	v_cmp_lt_i32_e32 vcc, 15, v137
	s_and_saveexec_b64 s[0:1], vcc
	s_xor_b64 s[0:1], exec, s[0:1]
	v_lshlrev_b32_e32 v132, 12, v135
	v_add3_u32 v132, v132, v137, -16
	v_ashrrev_i32_e32 v133, 31, v132
	v_lshlrev_b64 v[132:133], 12, v[132:133]
	v_lshl_add_u64 v[132:133], s[88:89], 0, v[132:133]
	s_andn2_saveexec_b64 s[0:1], s[0:1]
	v_lshlrev_b32_e32 v132, 14, v135
	v_lshl_add_u32 v132, v137, 10, v132
	v_ashrrev_i32_e32 v133, 31, v132
	v_lshl_add_u64 v[132:133], v[132:133], 2, s[16:17]
	s_or_b64 exec, exec, s[0:1]
	v_lshl_add_u64 v[132:133], v[130:131], 2, v[132:133]
	global_load_dword v183, v[132:133], off
	global_load_dword v143, v[132:133], off offset:128
	v_or_b32_e32 v142, 25, v136
	v_min_i32_e32 v132, 0x403f, v142
	v_mul_hi_i32 v133, v132, s83
	v_lshrrev_b32_e32 v135, 31, v133
	v_ashrrev_i32_e32 v133, 11, v133
	v_add_u32_e32 v135, v133, v135
	v_mad_i32_i24 v137, v135, s84, v132
	v_cmp_lt_i32_e32 vcc, 15, v137
	s_and_saveexec_b64 s[0:1], vcc
	s_xor_b64 s[0:1], exec, s[0:1]
	v_lshlrev_b32_e32 v132, 12, v135
	v_add3_u32 v132, v132, v137, -16
	v_ashrrev_i32_e32 v133, 31, v132
	v_lshlrev_b64 v[132:133], 12, v[132:133]
	v_lshl_add_u64 v[132:133], s[88:89], 0, v[132:133]
	s_andn2_saveexec_b64 s[0:1], s[0:1]
	v_lshlrev_b32_e32 v132, 14, v135
	v_lshl_add_u32 v132, v137, 10, v132
	v_ashrrev_i32_e32 v133, 31, v132
	v_lshl_add_u64 v[132:133], v[132:133], 2, s[16:17]
	s_or_b64 exec, exec, s[0:1]
	v_lshl_add_u64 v[132:133], v[130:131], 2, v[132:133]
	global_load_dword v182, v[132:133], off
	global_load_dword v141, v[132:133], off offset:128
	v_or_b32_e32 v140, 26, v136
	v_min_i32_e32 v132, 0x403f, v140
	v_mul_hi_i32 v133, v132, s83
	v_lshrrev_b32_e32 v135, 31, v133
	v_ashrrev_i32_e32 v133, 11, v133
	v_add_u32_e32 v135, v133, v135
	v_mad_i32_i24 v137, v135, s84, v132
	v_cmp_lt_i32_e32 vcc, 15, v137
	s_and_saveexec_b64 s[0:1], vcc
	s_xor_b64 s[0:1], exec, s[0:1]
	v_lshlrev_b32_e32 v132, 12, v135
	v_add3_u32 v132, v132, v137, -16
	v_ashrrev_i32_e32 v133, 31, v132
	v_lshlrev_b64 v[132:133], 12, v[132:133]
	v_lshl_add_u64 v[132:133], s[88:89], 0, v[132:133]
	s_andn2_saveexec_b64 s[0:1], s[0:1]
	v_lshlrev_b32_e32 v132, 14, v135
	v_lshl_add_u32 v132, v137, 10, v132
	v_ashrrev_i32_e32 v133, 31, v132
	v_lshl_add_u64 v[132:133], v[132:133], 2, s[16:17]
	s_or_b64 exec, exec, s[0:1]
	v_lshl_add_u64 v[132:133], v[130:131], 2, v[132:133]
	global_load_dword v179, v[132:133], off
	global_load_dword v139, v[132:133], off offset:128
	v_or_b32_e32 v138, 27, v136
	v_min_i32_e32 v132, 0x403f, v138
	v_mul_hi_i32 v133, v132, s83
	v_lshrrev_b32_e32 v135, 31, v133
	v_ashrrev_i32_e32 v133, 11, v133
	v_add_u32_e32 v135, v133, v135
	v_mad_i32_i24 v137, v135, s84, v132
	v_cmp_lt_i32_e32 vcc, 15, v137
	s_and_saveexec_b64 s[0:1], vcc
	s_xor_b64 s[0:1], exec, s[0:1]
	v_lshlrev_b32_e32 v132, 12, v135
	v_add3_u32 v132, v132, v137, -16
	v_ashrrev_i32_e32 v133, 31, v132
	v_lshlrev_b64 v[132:133], 12, v[132:133]
	v_lshl_add_u64 v[132:133], s[88:89], 0, v[132:133]
	s_andn2_saveexec_b64 s[0:1], s[0:1]
	v_lshlrev_b32_e32 v132, 14, v135
	v_lshl_add_u32 v132, v137, 10, v132
	v_ashrrev_i32_e32 v133, 31, v132
	v_lshl_add_u64 v[132:133], v[132:133], 2, s[16:17]
	s_or_b64 exec, exec, s[0:1]
	v_lshl_add_u64 v[132:133], v[130:131], 2, v[132:133]
	global_load_dword v178, v[132:133], off
	global_load_dword v177, v[132:133], off offset:128
	v_cmp_gt_i32_e32 vcc, s85, v136
	s_nop 1
	v_cndmask_b32_e32 v132, v181, v136, vcc
	v_mul_hi_i32 v133, v132, s83
	v_lshrrev_b32_e32 v135, 31, v133
	v_ashrrev_i32_e32 v133, 11, v133
	v_add_u32_e32 v135, v133, v135
	v_mad_i32_i24 v137, v135, s84, v132
	v_cmp_lt_i32_e64 s[0:1], 15, v137
	s_and_saveexec_b64 s[2:3], s[0:1]
	s_xor_b64 s[0:1], exec, s[2:3]
	v_lshlrev_b32_e32 v132, 12, v135
	v_add3_u32 v132, v132, v137, -16
	v_ashrrev_i32_e32 v133, 31, v132
	v_lshlrev_b64 v[132:133], 12, v[132:133]
	v_lshl_add_u64 v[132:133], s[88:89], 0, v[132:133]
	s_andn2_saveexec_b64 s[0:1], s[0:1]
	v_lshlrev_b32_e32 v132, 14, v135
	v_lshl_add_u32 v132, v137, 10, v132
	v_ashrrev_i32_e32 v133, 31, v132
	v_lshl_add_u64 v[132:133], v[132:133], 2, s[16:17]
	s_or_b64 exec, exec, s[0:1]
	v_ashrrev_i32_e32 v137, 31, v136
	v_lshlrev_b64 v[168:169], 11, v[136:137]
	v_readlane_b32 s44, v239, 4
	v_lshl_add_u64 v[168:169], s[62:63], 0, v[168:169]
	s_waitcnt vmcnt(31)
	v_add_f32_e32 v137, v114, v134
	v_lshlrev_b64 v[134:135], 2, v[130:131]
	v_readlane_b32 s50, v239, 10
	v_readlane_b32 s51, v239, 11
	v_lshl_add_u64 v[168:169], v[130:131], 1, v[168:169]
	v_lshl_add_u64 v[170:171], v[132:133], 0, v[134:135]
	v_lshl_add_u64 v[132:133], s[50:51], 0, v[134:135]
	global_load_dword v242, v[132:133], off
	global_load_dword v243, v[132:133], off offset:128
	s_waitcnt vmcnt(0)
	v_readlane_b32 s45, v239, 5
	v_readlane_b32 s46, v239, 6
	v_readlane_b32 s47, v239, 7
	v_readlane_b32 s48, v239, 8
	v_readlane_b32 s49, v239, 9
	v_readlane_b32 s52, v239, 12
	v_readlane_b32 s53, v239, 13
	v_readlane_b32 s54, v239, 14
	v_readlane_b32 s55, v239, 15
	v_readlane_b32 s56, v239, 16
	v_readlane_b32 s57, v239, 17
	v_readlane_b32 s58, v239, 18
	v_readlane_b32 s59, v239, 19
	s_and_saveexec_b64 s[0:1], vcc
	s_cbranch_execz .LBB0_3711
	global_store_dword v[170:171], v137, off
	v_mul_f32_e32 v114, v137, v242
	v_cvt_pk_bf16_f32 v114, v114, s0
	global_store_short v[168:169], v114, off

.LBB0_4025:
	s_or_b64 exec, exec, s[0:1]
	v_lshlrev_b32_e32 v66, 1, v175
	v_lshlrev_b32_e32 v104, 1, v172
	v_and_b32_e32 v66, 32, v66
	v_and_b32_e32 v104, 24, v104
	v_and_b32_e32 v105, 3, v172
	v_or3_b32 v66, v105, v104, v66
	v_and_b32_e32 v105, 64, v200
	v_mul_f32_e32 v71, v71, v71
	v_mul_f32_e32 v70, v70, v70
	v_xor_b32_e32 v104, 16, v200
	v_add_u32_e32 v109, 64, v105
	v_fmac_f32_e32 v71, v83, v83
	v_fmac_f32_e32 v70, v82, v82
	v_mul_f32_e32 v82, v128, v128
	v_mul_f32_e32 v83, v178, v178
	v_mul_f32_e32 v98, v168, v168
	v_mul_f32_e32 v99, v176, v176
	v_and_b32_e32 v100, 16, v172
	v_cmp_lt_i32_e32 vcc, v104, v109
	v_fmac_f32_e32 v82, v138, v138
	v_fmac_f32_e32 v83, v169, v169
	v_fmac_f32_e32 v98, v170, v170
	v_fmac_f32_e32 v99, v137, v137
	v_cndmask_b32_e32 v104, v200, v104, vcc
	v_cmp_eq_u32_e32 vcc, 0, v100
	v_mul_f32_e32 v81, v81, v81
	v_lshlrev_b32_e32 v104, 2, v104
	v_cndmask_b32_e32 v100, v99, v83, vcc
	v_fmac_f32_e32 v81, v80, v80
	v_cndmask_b32_e32 v80, v83, v99, vcc
	v_cndmask_b32_e32 v83, v98, v82, vcc
	ds_bpermute_b32 v83, v104, v83
	v_mul_f32_e32 v67, v95, v95
	v_mul_f32_e32 v95, v161, v161
	v_fmac_f32_e32 v95, v160, v160
	v_cndmask_b32_e32 v82, v82, v98, vcc
	s_waitcnt lgkmcnt(0)
	v_add_f32_e32 v82, v82, v83
	v_cndmask_b32_e32 v83, v95, v70, vcc
	ds_bpermute_b32 v83, v104, v83
	v_mul_f32_e32 v69, v78, v78
	v_fmac_f32_e32 v69, v92, v92
	v_mul_f32_e32 v73, v73, v73
	v_mul_f32_e32 v92, v155, v155
	v_fmac_f32_e32 v73, v87, v87
	v_fmac_f32_e32 v92, v154, v154
	v_cndmask_b32_e32 v70, v70, v95, vcc
	s_waitcnt lgkmcnt(0)
	v_add_f32_e32 v70, v70, v83
	v_cndmask_b32_e32 v83, v92, v73, vcc
	ds_bpermute_b32 v83, v104, v83
	v_mul_f32_e32 v75, v75, v75
	v_mul_f32_e32 v76, v76, v76
	v_fmac_f32_e32 v75, v89, v89
	v_mul_f32_e32 v89, v149, v149
	v_fmac_f32_e32 v76, v90, v90
	v_fmac_f32_e32 v89, v148, v148
	v_cndmask_b32_e32 v73, v73, v92, vcc
	s_waitcnt lgkmcnt(0)
	v_add_f32_e32 v73, v73, v83
	v_cndmask_b32_e32 v83, v89, v76, vcc
	ds_bpermute_b32 v83, v104, v83
	v_mul_f32_e32 v72, v72, v72
	v_mul_f32_e32 v68, v79, v79
	v_fmac_f32_e32 v72, v86, v86
	v_mul_f32_e32 v86, v143, v143
	v_fmac_f32_e32 v68, v93, v93
	v_mul_f32_e32 v77, v77, v77
	v_fmac_f32_e32 v86, v142, v142
	v_cndmask_b32_e32 v76, v76, v89, vcc
	v_fmac_f32_e32 v77, v91, v91
	v_mul_f32_e32 v74, v74, v74
	v_mul_f32_e32 v91, v153, v153
	s_waitcnt lgkmcnt(0)
	v_add_f32_e32 v76, v76, v83
	v_cndmask_b32_e32 v83, v86, v68, vcc
	v_fmac_f32_e32 v74, v88, v88
	v_mul_f32_e32 v78, v122, v122
	v_mul_f32_e32 v79, v124, v124
	v_mul_f32_e32 v88, v147, v147
	v_fmac_f32_e32 v91, v152, v152
	v_mul_f32_e32 v96, v163, v163
	v_mul_f32_e32 v97, v165, v165
	ds_bpermute_b32 v83, v104, v83
	v_fmac_f32_e32 v78, v85, v85
	v_fmac_f32_e32 v79, v84, v84
	v_mul_f32_e32 v87, v145, v145
	v_fmac_f32_e32 v88, v146, v146
	v_mul_f32_e32 v90, v151, v151
	v_mul_f32_e32 v93, v157, v157
	v_fmac_f32_e32 v96, v162, v162
	v_fmac_f32_e32 v97, v164, v164
	v_cndmask_b32_e32 v92, v91, v74, vcc
	v_fmac_f32_e32 v87, v144, v144
	v_fmac_f32_e32 v90, v150, v150
	v_fmac_f32_e32 v93, v156, v156
	ds_bpermute_b32 v100, v104, v100
	v_cndmask_b32_e32 v98, v97, v79, vcc
	v_cndmask_b32_e32 v99, v96, v78, vcc
	ds_bpermute_b32 v92, v104, v92
	v_cndmask_b32_e32 v89, v88, v77, vcc
	ds_bpermute_b32 v98, v104, v98
	ds_bpermute_b32 v99, v104, v99
	v_cndmask_b32_e32 v78, v78, v96, vcc
	v_cndmask_b32_e32 v96, v93, v72, vcc
	v_cndmask_b32_e32 v72, v72, v93, vcc
	v_cndmask_b32_e32 v93, v90, v75, vcc
	v_cndmask_b32_e32 v75, v75, v90, vcc
	ds_bpermute_b32 v89, v104, v89
	v_cndmask_b32_e32 v90, v87, v69, vcc
	s_lshl_b32 s0, s4, 2
	ds_bpermute_b32 v90, v104, v90
	v_cndmask_b32_e32 v68, v68, v86, vcc
	v_fmac_f32_e32 v67, v94, v94
	v_mul_f32_e32 v85, v141, v141
	v_mul_f32_e32 v94, v159, v159
	s_ashr_i32 s1, s0, 31
	s_waitcnt lgkmcnt(6)
	v_add_f32_e32 v68, v68, v83
	v_xor_b32_e32 v83, 8, v200
	v_mul_f32_e32 v84, v167, v167
	v_fmac_f32_e32 v85, v140, v140
	v_fmac_f32_e32 v94, v158, v158
	v_and_b32_e32 v101, 8, v172
	s_lshl_b64 s[8:9], s[0:1], 2
	v_cndmask_b32_e32 v74, v74, v91, vcc
	v_cmp_lt_i32_e64 s[0:1], v83, v109
	v_fmac_f32_e32 v84, v166, v166
	s_waitcnt lgkmcnt(5)
	v_add_f32_e32 v80, v80, v100
	v_cndmask_b32_e32 v79, v79, v97, vcc
	v_cndmask_b32_e32 v95, v94, v71, vcc
	s_waitcnt lgkmcnt(4)
	v_add_f32_e32 v74, v74, v92
	v_cndmask_b32_e32 v77, v77, v88, vcc
	v_cndmask_b32_e32 v86, v85, v67, vcc
	v_cndmask_b32_e64 v83, v200, v83, s[0:1]
	v_cmp_eq_u32_e64 s[2:3], 0, v101
	s_waitcnt lgkmcnt(3)
	v_add_f32_e32 v79, v79, v98
	s_waitcnt lgkmcnt(2)
	v_add_f32_e32 v78, v78, v99
	ds_bpermute_b32 v95, v104, v95
	ds_bpermute_b32 v96, v104, v96
	ds_bpermute_b32 v93, v104, v93
	s_waitcnt lgkmcnt(4)
	v_add_f32_e32 v77, v77, v89
	v_cndmask_b32_e32 v69, v69, v87, vcc
	ds_bpermute_b32 v86, v104, v86
	v_cndmask_b32_e32 v87, v84, v81, vcc
	v_lshlrev_b32_e32 v105, 2, v83
	v_cndmask_b32_e64 v83, v80, v74, s[2:3]
	s_waitcnt lgkmcnt(4)
	v_add_f32_e32 v69, v69, v90
	ds_bpermute_b32 v87, v104, v87
	v_cndmask_b32_e32 v81, v81, v84, vcc
	v_cndmask_b32_e64 v74, v74, v80, s[2:3]
	ds_bpermute_b32 v80, v105, v83
	v_cndmask_b32_e64 v84, v79, v76, s[2:3]
	v_cndmask_b32_e64 v76, v76, v79, s[2:3]
	v_cndmask_b32_e64 v79, v78, v77, s[2:3]
	v_cndmask_b32_e64 v77, v77, v78, s[2:3]
	ds_bpermute_b32 v78, v105, v79
	v_cndmask_b32_e64 v79, v70, v69, s[2:3]
	ds_bpermute_b32 v79, v105, v79
	v_cndmask_b32_e32 v71, v71, v94, vcc
	v_cndmask_b32_e32 v67, v67, v85, vcc
	s_waitcnt lgkmcnt(7)
	v_add_f32_e32 v71, v71, v95
	s_waitcnt lgkmcnt(6)
	v_add_f32_e32 v72, v72, v96
	s_waitcnt lgkmcnt(5)
	v_add_f32_e32 v75, v75, v93
	s_waitcnt lgkmcnt(4)
	v_add_f32_e32 v67, v67, v86
	s_waitcnt lgkmcnt(3)
	v_add_f32_e32 v81, v81, v87
	v_cndmask_b32_e64 v83, v82, v75, s[2:3]
	s_waitcnt lgkmcnt(2)
	v_add_f32_e32 v74, v74, v80
	v_cndmask_b32_e64 v80, v71, v68, s[2:3]
	v_cndmask_b32_e64 v69, v69, v70, s[2:3]
	v_cndmask_b32_e64 v70, v72, v67, s[2:3]
	v_cndmask_b32_e64 v67, v67, v72, s[2:3]
	v_xor_b32_e32 v72, 4, v200
	v_and_b32_e32 v102, 4, v172
	ds_bpermute_b32 v83, v105, v83
	ds_bpermute_b32 v80, v105, v80
	v_cndmask_b32_e64 v68, v68, v71, s[2:3]
	ds_bpermute_b32 v70, v105, v70
	v_cndmask_b32_e64 v71, v73, v81, s[2:3]
	v_cmp_lt_i32_e64 s[0:1], v72, v109
	s_waitcnt lgkmcnt(3)
	v_add_f32_e32 v69, v69, v79
	ds_bpermute_b32 v71, v105, v71
	v_cndmask_b32_e64 v72, v200, v72, s[0:1]
	v_cmp_eq_u32_e64 s[4:5], 0, v102
	ds_bpermute_b32 v84, v105, v84
	v_lshlrev_b32_e32 v106, 2, v72
	v_cndmask_b32_e64 v72, v74, v69, s[4:5]
	ds_bpermute_b32 v72, v106, v72
	v_cndmask_b32_e64 v75, v75, v82, s[2:3]
	s_waitcnt lgkmcnt(5)
	v_add_f32_e32 v75, v75, v83
	s_waitcnt lgkmcnt(4)
	v_add_f32_e32 v68, v68, v80
	s_waitcnt lgkmcnt(3)
	v_add_f32_e32 v67, v67, v70
	v_cndmask_b32_e64 v70, v81, v73, s[2:3]
	s_waitcnt lgkmcnt(2)
	v_add_f32_e32 v70, v70, v71
	v_cndmask_b32_e64 v71, v75, v68, s[4:5]
	s_waitcnt lgkmcnt(1)
	v_add_f32_e32 v76, v76, v84
	v_add_f32_e32 v77, v77, v78
	v_cndmask_b32_e64 v69, v69, v74, s[4:5]
	ds_bpermute_b32 v71, v106, v71
	s_waitcnt lgkmcnt(1)
	v_add_f32_e32 v69, v69, v72
	v_cndmask_b32_e64 v72, v76, v67, s[4:5]
	v_cndmask_b32_e64 v73, v77, v70, s[4:5]
	ds_bpermute_b32 v72, v106, v72
	ds_bpermute_b32 v73, v106, v73
	v_cndmask_b32_e64 v68, v68, v75, s[4:5]
	s_waitcnt lgkmcnt(2)
	v_add_f32_e32 v68, v68, v71
	v_xor_b32_e32 v71, 2, v200
	v_and_b32_e32 v103, 2, v172
	v_cndmask_b32_e64 v67, v67, v76, s[4:5]
	v_cndmask_b32_e64 v70, v70, v77, s[4:5]
	v_cmp_lt_i32_e64 s[0:1], v71, v109
	s_waitcnt lgkmcnt(1)
	v_add_f32_e32 v67, v67, v72
	s_waitcnt lgkmcnt(0)
	v_add_f32_e32 v70, v70, v73
	v_cndmask_b32_e64 v71, v200, v71, s[0:1]
	v_cmp_eq_u32_e64 s[6:7], 0, v103
	v_lshlrev_b32_e32 v107, 2, v71
	v_and_b32_e32 v108, 1, v172
	v_cndmask_b32_e64 v71, v69, v67, s[6:7]
	v_cndmask_b32_e64 v72, v68, v70, s[6:7]
	ds_bpermute_b32 v71, v107, v71
	ds_bpermute_b32 v72, v107, v72
	v_cndmask_b32_e64 v67, v67, v69, s[6:7]
	v_xor_b32_e32 v69, 1, v200
	s_add_u32 s10, s12, s8
	v_cndmask_b32_e64 v68, v70, v68, s[6:7]
	v_cmp_lt_i32_e64 s[0:1], v69, v109
	s_addc_u32 s11, s13, s9
	s_waitcnt lgkmcnt(1)
	v_add_f32_e32 v67, v67, v71
	s_waitcnt lgkmcnt(0)
	v_add_f32_e32 v70, v68, v72
	v_cmp_eq_u32_e64 s[8:9], 0, v108
	v_cndmask_b32_e64 v69, v200, v69, s[0:1]
	v_lshlrev_b32_e32 v108, 2, v69
	v_cndmask_b32_e64 v68, v67, v70, s[8:9]
	ds_bpermute_b32 v71, v108, v68
	v_or3_b32 v66, v66, v173, v174
	v_lshlrev_b32_e32 v0, 2, v0
	v_lshl_add_u64 v[68:69], s[10:11], 0, v[0:1]
	v_cndmask_b32_e64 v0, v70, v67, s[8:9]
	v_ashrrev_i32_e32 v67, 31, v66
	s_waitcnt lgkmcnt(0)
	v_add_f32_e32 v0, v0, v71
	v_lshlrev_b64 v[70:71], 6, v[66:67]
	v_or_b32_e32 v100, 64, v136
	v_lshl_add_u64 v[70:71], v[68:69], 0, v[70:71]
	v_min_i32_e32 v67, 0x403f, v100
	global_store_dword v[70:71], v0, off
	s_cmp_lg_u32 s32, 0
	s_cbranch_scc0 .Lrt1_c
	s_branch .LBB0_3578
.Lrt1_c:
	v_mul_hi_i32 v0, v67, s83
	v_lshrrev_b32_e32 v70, 31, v0
	v_ashrrev_i32_e32 v0, 11, v0
	v_add_u32_e32 v0, v0, v70
	v_mad_i32_i24 v67, v0, s84, v67
	v_cmp_lt_i32_e64 s[0:1], 15, v67
	s_and_saveexec_b64 s[10:11], s[0:1]
	s_xor_b64 s[0:1], exec, s[10:11]
	v_lshlrev_b32_e32 v0, 12, v0
	v_add3_u32 v70, v0, v67, -16
	v_ashrrev_i32_e32 v71, 31, v70
	v_lshlrev_b64 v[70:71], 12, v[70:71]
	v_lshl_add_u64 v[70:71], s[88:89], 0, v[70:71]
	s_andn2_saveexec_b64 s[0:1], s[0:1]
	v_lshlrev_b32_e32 v0, 14, v0
	v_lshl_add_u32 v70, v67, 10, v0
	v_ashrrev_i32_e32 v71, 31, v70
	v_lshl_add_u64 v[70:71], v[70:71], 2, s[16:17]
	s_or_b64 exec, exec, s[0:1]
	v_lshl_add_u64 v[70:71], v[130:131], 2, v[70:71]
	global_load_dword v0, v[70:71], off
	global_load_dword v67, v[70:71], off offset:128
	v_or_b32_e32 v98, 0x41, v136
	v_min_i32_e32 v70, 0x403f, v98
	v_mul_hi_i32 v71, v70, s83
	v_lshrrev_b32_e32 v72, 31, v71
	v_ashrrev_i32_e32 v71, 11, v71
	v_add_u32_e32 v72, v71, v72
	v_mad_i32_i24 v73, v72, s84, v70
	v_cmp_lt_i32_e64 s[0:1], 15, v73
	s_and_saveexec_b64 s[10:11], s[0:1]
	s_xor_b64 s[0:1], exec, s[10:11]
	v_lshlrev_b32_e32 v70, 12, v72
	v_add3_u32 v70, v70, v73, -16
	v_ashrrev_i32_e32 v71, 31, v70
	v_lshlrev_b64 v[70:71], 12, v[70:71]
	v_lshl_add_u64 v[70:71], s[88:89], 0, v[70:71]
	s_andn2_saveexec_b64 s[0:1], s[0:1]
	v_lshlrev_b32_e32 v70, 14, v72
	v_lshl_add_u32 v70, v73, 10, v70
	v_ashrrev_i32_e32 v71, 31, v70
	v_lshl_add_u64 v[70:71], v[70:71], 2, s[16:17]
	s_or_b64 exec, exec, s[0:1]
	v_lshl_add_u64 v[70:71], v[130:131], 2, v[70:71]
	global_load_dword v124, v[70:71], off
	global_load_dword v97, v[70:71], off offset:128
	v_or_b32_e32 v96, 0x42, v136
	v_min_i32_e32 v70, 0x403f, v96
	v_mul_hi_i32 v71, v70, s83
	v_lshrrev_b32_e32 v72, 31, v71
	v_ashrrev_i32_e32 v71, 11, v71
	v_add_u32_e32 v72, v71, v72
	v_mad_i32_i24 v73, v72, s84, v70
	v_cmp_lt_i32_e64 s[0:1], 15, v73
	s_and_saveexec_b64 s[10:11], s[0:1]
	s_xor_b64 s[0:1], exec, s[10:11]
	v_lshlrev_b32_e32 v70, 12, v72
	v_add3_u32 v70, v70, v73, -16
	v_ashrrev_i32_e32 v71, 31, v70
	v_lshlrev_b64 v[70:71], 12, v[70:71]
	v_lshl_add_u64 v[70:71], s[88:89], 0, v[70:71]
	s_andn2_saveexec_b64 s[0:1], s[0:1]
	v_lshlrev_b32_e32 v70, 14, v72
	v_lshl_add_u32 v70, v73, 10, v70
	v_ashrrev_i32_e32 v71, 31, v70
	v_lshl_add_u64 v[70:71], v[70:71], 2, s[16:17]
	s_or_b64 exec, exec, s[0:1]
	v_lshl_add_u64 v[70:71], v[130:131], 2, v[70:71]
	global_load_dword v123, v[70:71], off
	global_load_dword v95, v[70:71], off offset:128
	v_or_b32_e32 v94, 0x43, v136
	v_min_i32_e32 v70, 0x403f, v94
	v_mul_hi_i32 v71, v70, s83
	v_lshrrev_b32_e32 v72, 31, v71
	v_ashrrev_i32_e32 v71, 11, v71
	v_add_u32_e32 v72, v71, v72
	v_mad_i32_i24 v73, v72, s84, v70
	v_cmp_lt_i32_e64 s[0:1], 15, v73
	s_and_saveexec_b64 s[10:11], s[0:1]
	s_xor_b64 s[0:1], exec, s[10:11]
	v_lshlrev_b32_e32 v70, 12, v72
	v_add3_u32 v70, v70, v73, -16
	v_ashrrev_i32_e32 v71, 31, v70
	v_lshlrev_b64 v[70:71], 12, v[70:71]
	v_lshl_add_u64 v[70:71], s[88:89], 0, v[70:71]
	s_andn2_saveexec_b64 s[0:1], s[0:1]
	v_lshlrev_b32_e32 v70, 14, v72
	v_lshl_add_u32 v70, v73, 10, v70
	v_ashrrev_i32_e32 v71, 31, v70
	v_lshl_add_u64 v[70:71], v[70:71], 2, s[16:17]
	s_or_b64 exec, exec, s[0:1]
	v_lshl_add_u64 v[70:71], v[130:131], 2, v[70:71]
	global_load_dword v122, v[70:71], off
	global_load_dword v93, v[70:71], off offset:128
	v_or_b32_e32 v92, 0x48, v136
	v_min_i32_e32 v70, 0x403f, v92
	v_mul_hi_i32 v71, v70, s83
	v_lshrrev_b32_e32 v72, 31, v71
	v_ashrrev_i32_e32 v71, 11, v71
	v_add_u32_e32 v72, v71, v72
	v_mad_i32_i24 v73, v72, s84, v70
	v_cmp_lt_i32_e64 s[0:1], 15, v73
	s_and_saveexec_b64 s[10:11], s[0:1]
	s_xor_b64 s[0:1], exec, s[10:11]
	v_lshlrev_b32_e32 v70, 12, v72
	v_add3_u32 v70, v70, v73, -16
	v_ashrrev_i32_e32 v71, 31, v70
	v_lshlrev_b64 v[70:71], 12, v[70:71]
	v_lshl_add_u64 v[70:71], s[88:89], 0, v[70:71]
	s_andn2_saveexec_b64 s[0:1], s[0:1]
	v_lshlrev_b32_e32 v70, 14, v72
	v_lshl_add_u32 v70, v73, 10, v70
	v_ashrrev_i32_e32 v71, 31, v70
	v_lshl_add_u64 v[70:71], v[70:71], 2, s[16:17]
	s_or_b64 exec, exec, s[0:1]
	v_lshl_add_u64 v[70:71], v[130:131], 2, v[70:71]
	global_load_dword v121, v[70:71], off
	global_load_dword v91, v[70:71], off offset:128
	v_or_b32_e32 v90, 0x49, v136
	v_min_i32_e32 v70, 0x403f, v90
	v_mul_hi_i32 v71, v70, s83
	v_lshrrev_b32_e32 v72, 31, v71
	v_ashrrev_i32_e32 v71, 11, v71
	v_add_u32_e32 v72, v71, v72
	v_mad_i32_i24 v73, v72, s84, v70
	v_cmp_lt_i32_e64 s[0:1], 15, v73
	s_and_saveexec_b64 s[10:11], s[0:1]
	s_xor_b64 s[0:1], exec, s[10:11]
	v_lshlrev_b32_e32 v70, 12, v72
	v_add3_u32 v70, v70, v73, -16
	v_ashrrev_i32_e32 v71, 31, v70
	v_lshlrev_b64 v[70:71], 12, v[70:71]
	v_lshl_add_u64 v[70:71], s[88:89], 0, v[70:71]
	s_andn2_saveexec_b64 s[0:1], s[0:1]
	v_lshlrev_b32_e32 v70, 14, v72
	v_lshl_add_u32 v70, v73, 10, v70
	v_ashrrev_i32_e32 v71, 31, v70
	v_lshl_add_u64 v[70:71], v[70:71], 2, s[16:17]
	s_or_b64 exec, exec, s[0:1]
	v_lshl_add_u64 v[70:71], v[130:131], 2, v[70:71]
	global_load_dword v120, v[70:71], off
	global_load_dword v89, v[70:71], off offset:128
	v_or_b32_e32 v88, 0x4a, v136
	v_min_i32_e32 v70, 0x403f, v88
	v_mul_hi_i32 v71, v70, s83
	v_lshrrev_b32_e32 v72, 31, v71
	v_ashrrev_i32_e32 v71, 11, v71
	v_add_u32_e32 v72, v71, v72
	v_mad_i32_i24 v73, v72, s84, v70
	v_cmp_lt_i32_e64 s[0:1], 15, v73
	s_and_saveexec_b64 s[10:11], s[0:1]
	s_xor_b64 s[0:1], exec, s[10:11]
	v_lshlrev_b32_e32 v70, 12, v72
	v_add3_u32 v70, v70, v73, -16
	v_ashrrev_i32_e32 v71, 31, v70
	v_lshlrev_b64 v[70:71], 12, v[70:71]
	v_lshl_add_u64 v[70:71], s[88:89], 0, v[70:71]
	s_andn2_saveexec_b64 s[0:1], s[0:1]
	v_lshlrev_b32_e32 v70, 14, v72
	v_lshl_add_u32 v70, v73, 10, v70
	v_ashrrev_i32_e32 v71, 31, v70
	v_lshl_add_u64 v[70:71], v[70:71], 2, s[16:17]
	s_or_b64 exec, exec, s[0:1]
	v_lshl_add_u64 v[70:71], v[130:131], 2, v[70:71]
	global_load_dword v119, v[70:71], off
	global_load_dword v87, v[70:71], off offset:128
	v_or_b32_e32 v86, 0x4b, v136
	v_min_i32_e32 v70, 0x403f, v86
	v_mul_hi_i32 v71, v70, s83
	v_lshrrev_b32_e32 v72, 31, v71
	v_ashrrev_i32_e32 v71, 11, v71
	v_add_u32_e32 v72, v71, v72
	v_mad_i32_i24 v73, v72, s84, v70
	v_cmp_lt_i32_e64 s[0:1], 15, v73
	s_and_saveexec_b64 s[10:11], s[0:1]
	s_xor_b64 s[0:1], exec, s[10:11]
	v_lshlrev_b32_e32 v70, 12, v72
	v_add3_u32 v70, v70, v73, -16
	v_ashrrev_i32_e32 v71, 31, v70
	v_lshlrev_b64 v[70:71], 12, v[70:71]
	v_lshl_add_u64 v[70:71], s[88:89], 0, v[70:71]
	s_andn2_saveexec_b64 s[0:1], s[0:1]
	v_lshlrev_b32_e32 v70, 14, v72
	v_lshl_add_u32 v70, v73, 10, v70
	v_ashrrev_i32_e32 v71, 31, v70
	v_lshl_add_u64 v[70:71], v[70:71], 2, s[16:17]
	s_or_b64 exec, exec, s[0:1]
	v_lshl_add_u64 v[70:71], v[130:131], 2, v[70:71]
	global_load_dword v118, v[70:71], off
	global_load_dword v85, v[70:71], off offset:128
	v_or_b32_e32 v84, 0x50, v136
	v_min_i32_e32 v70, 0x403f, v84
	v_mul_hi_i32 v71, v70, s83
	v_lshrrev_b32_e32 v72, 31, v71
	v_ashrrev_i32_e32 v71, 11, v71
	v_add_u32_e32 v72, v71, v72
	v_mad_i32_i24 v73, v72, s84, v70
	v_cmp_lt_i32_e64 s[0:1], 15, v73
	s_and_saveexec_b64 s[10:11], s[0:1]
	s_xor_b64 s[0:1], exec, s[10:11]
	v_lshlrev_b32_e32 v70, 12, v72
	v_add3_u32 v70, v70, v73, -16
	v_ashrrev_i32_e32 v71, 31, v70
	v_lshlrev_b64 v[70:71], 12, v[70:71]
	v_lshl_add_u64 v[70:71], s[88:89], 0, v[70:71]
	s_andn2_saveexec_b64 s[0:1], s[0:1]
	v_lshlrev_b32_e32 v70, 14, v72
	v_lshl_add_u32 v70, v73, 10, v70
	v_ashrrev_i32_e32 v71, 31, v70
	v_lshl_add_u64 v[70:71], v[70:71], 2, s[16:17]
	s_or_b64 exec, exec, s[0:1]
	v_lshl_add_u64 v[70:71], v[130:131], 2, v[70:71]
	global_load_dword v117, v[70:71], off
	global_load_dword v83, v[70:71], off offset:128
	v_or_b32_e32 v82, 0x51, v136
	v_min_i32_e32 v70, 0x403f, v82
	v_mul_hi_i32 v71, v70, s83
	v_lshrrev_b32_e32 v72, 31, v71
	v_ashrrev_i32_e32 v71, 11, v71
	v_add_u32_e32 v72, v71, v72
	v_mad_i32_i24 v73, v72, s84, v70
	v_cmp_lt_i32_e64 s[0:1], 15, v73
	s_and_saveexec_b64 s[10:11], s[0:1]
	s_xor_b64 s[0:1], exec, s[10:11]
	v_lshlrev_b32_e32 v70, 12, v72
	v_add3_u32 v70, v70, v73, -16
	v_ashrrev_i32_e32 v71, 31, v70
	v_lshlrev_b64 v[70:71], 12, v[70:71]
	v_lshl_add_u64 v[70:71], s[88:89], 0, v[70:71]
	s_andn2_saveexec_b64 s[0:1], s[0:1]
	v_lshlrev_b32_e32 v70, 14, v72
	v_lshl_add_u32 v70, v73, 10, v70
	v_ashrrev_i32_e32 v71, 31, v70
	v_lshl_add_u64 v[70:71], v[70:71], 2, s[16:17]
	s_or_b64 exec, exec, s[0:1]
	v_lshl_add_u64 v[70:71], v[130:131], 2, v[70:71]
	global_load_dword v116, v[70:71], off
	global_load_dword v81, v[70:71], off offset:128
	v_or_b32_e32 v80, 0x52, v136
	v_min_i32_e32 v70, 0x403f, v80
	v_mul_hi_i32 v71, v70, s83
	v_lshrrev_b32_e32 v72, 31, v71
	v_ashrrev_i32_e32 v71, 11, v71
	v_add_u32_e32 v72, v71, v72
	v_mad_i32_i24 v73, v72, s84, v70
	v_cmp_lt_i32_e64 s[0:1], 15, v73
	s_and_saveexec_b64 s[10:11], s[0:1]
	s_xor_b64 s[0:1], exec, s[10:11]
	v_lshlrev_b32_e32 v70, 12, v72
	v_add3_u32 v70, v70, v73, -16
	v_ashrrev_i32_e32 v71, 31, v70
	v_lshlrev_b64 v[70:71], 12, v[70:71]
	v_lshl_add_u64 v[70:71], s[88:89], 0, v[70:71]
	s_andn2_saveexec_b64 s[0:1], s[0:1]
	v_lshlrev_b32_e32 v70, 14, v72
	v_lshl_add_u32 v70, v73, 10, v70
	v_ashrrev_i32_e32 v71, 31, v70
	v_lshl_add_u64 v[70:71], v[70:71], 2, s[16:17]
	s_or_b64 exec, exec, s[0:1]
	v_lshl_add_u64 v[70:71], v[130:131], 2, v[70:71]
	global_load_dword v115, v[70:71], off
	global_load_dword v79, v[70:71], off offset:128
	v_or_b32_e32 v78, 0x53, v136
	v_min_i32_e32 v70, 0x403f, v78
	v_mul_hi_i32 v71, v70, s83
	v_lshrrev_b32_e32 v72, 31, v71
	v_ashrrev_i32_e32 v71, 11, v71
	v_add_u32_e32 v72, v71, v72
	v_mad_i32_i24 v73, v72, s84, v70
	v_cmp_lt_i32_e64 s[0:1], 15, v73
	s_and_saveexec_b64 s[10:11], s[0:1]
	s_xor_b64 s[0:1], exec, s[10:11]
	v_lshlrev_b32_e32 v70, 12, v72
	v_add3_u32 v70, v70, v73, -16
	v_ashrrev_i32_e32 v71, 31, v70
	v_lshlrev_b64 v[70:71], 12, v[70:71]
	v_lshl_add_u64 v[70:71], s[88:89], 0, v[70:71]
	s_andn2_saveexec_b64 s[0:1], s[0:1]
	v_lshlrev_b32_e32 v70, 14, v72
	v_lshl_add_u32 v70, v73, 10, v70
	v_ashrrev_i32_e32 v71, 31, v70
	v_lshl_add_u64 v[70:71], v[70:71], 2, s[16:17]
	s_or_b64 exec, exec, s[0:1]
	v_lshl_add_u64 v[70:71], v[130:131], 2, v[70:71]
	global_load_dword v114, v[70:71], off
	global_load_dword v77, v[70:71], off offset:128
	v_or_b32_e32 v76, 0x58, v136
	v_min_i32_e32 v70, 0x403f, v76
	v_mul_hi_i32 v71, v70, s83
	v_lshrrev_b32_e32 v72, 31, v71
	v_ashrrev_i32_e32 v71, 11, v71
	v_add_u32_e32 v72, v71, v72
	v_mad_i32_i24 v73, v72, s84, v70
	v_cmp_lt_i32_e64 s[0:1], 15, v73
	s_and_saveexec_b64 s[10:11], s[0:1]
	s_xor_b64 s[0:1], exec, s[10:11]
	v_lshlrev_b32_e32 v70, 12, v72
	v_add3_u32 v70, v70, v73, -16
	v_ashrrev_i32_e32 v71, 31, v70
	v_lshlrev_b64 v[70:71], 12, v[70:71]
	v_lshl_add_u64 v[70:71], s[88:89], 0, v[70:71]
	s_andn2_saveexec_b64 s[0:1], s[0:1]
	v_lshlrev_b32_e32 v70, 14, v72
	v_lshl_add_u32 v70, v73, 10, v70
	v_ashrrev_i32_e32 v71, 31, v70
	v_lshl_add_u64 v[70:71], v[70:71], 2, s[16:17]
	s_or_b64 exec, exec, s[0:1]
	v_lshl_add_u64 v[70:71], v[130:131], 2, v[70:71]
	global_load_dword v113, v[70:71], off
	global_load_dword v75, v[70:71], off offset:128
	v_or_b32_e32 v74, 0x59, v136
	v_min_i32_e32 v70, 0x403f, v74
	v_mul_hi_i32 v71, v70, s83
	v_lshrrev_b32_e32 v72, 31, v71
	v_ashrrev_i32_e32 v71, 11, v71
	v_add_u32_e32 v72, v71, v72
	v_mad_i32_i24 v73, v72, s84, v70
	v_cmp_lt_i32_e64 s[0:1], 15, v73
	s_and_saveexec_b64 s[10:11], s[0:1]
	s_xor_b64 s[0:1], exec, s[10:11]
	v_lshlrev_b32_e32 v70, 12, v72
	v_add3_u32 v70, v70, v73, -16
	v_ashrrev_i32_e32 v71, 31, v70
	v_lshlrev_b64 v[70:71], 12, v[70:71]
	v_lshl_add_u64 v[70:71], s[88:89], 0, v[70:71]
	s_andn2_saveexec_b64 s[0:1], s[0:1]
	v_lshlrev_b32_e32 v70, 14, v72
	v_lshl_add_u32 v70, v73, 10, v70
	v_ashrrev_i32_e32 v71, 31, v70
	v_lshl_add_u64 v[70:71], v[70:71], 2, s[16:17]
	s_or_b64 exec, exec, s[0:1]
	v_lshl_add_u64 v[70:71], v[130:131], 2, v[70:71]
	global_load_dword v112, v[70:71], off
	global_load_dword v73, v[70:71], off offset:128
	v_or_b32_e32 v72, 0x5a, v136
	v_min_i32_e32 v70, 0x403f, v72
	v_mul_hi_i32 v71, v70, s83
	v_lshrrev_b32_e32 v99, 31, v71
	v_ashrrev_i32_e32 v71, 11, v71
	v_add_u32_e32 v99, v71, v99
	v_mad_i32_i24 v101, v99, s84, v70
	v_cmp_lt_i32_e64 s[0:1], 15, v101
	s_and_saveexec_b64 s[10:11], s[0:1]
	s_xor_b64 s[0:1], exec, s[10:11]
	v_lshlrev_b32_e32 v70, 12, v99
	v_add3_u32 v70, v70, v101, -16
	v_ashrrev_i32_e32 v71, 31, v70
	v_lshlrev_b64 v[70:71], 12, v[70:71]
	v_lshl_add_u64 v[70:71], s[88:89], 0, v[70:71]
	s_andn2_saveexec_b64 s[0:1], s[0:1]
	v_lshlrev_b32_e32 v70, 14, v99
	v_lshl_add_u32 v70, v101, 10, v70
	v_ashrrev_i32_e32 v71, 31, v70
	v_lshl_add_u64 v[70:71], v[70:71], 2, s[16:17]
	s_or_b64 exec, exec, s[0:1]
	v_lshl_add_u64 v[70:71], v[130:131], 2, v[70:71]
	global_load_dword v111, v[70:71], off
	s_nop 0
	global_load_dword v71, v[70:71], off offset:128
	v_or_b32_e32 v70, 0x5b, v136
	v_min_i32_e32 v101, 0x403f, v70
	v_mul_hi_i32 v99, v101, s83
	v_lshrrev_b32_e32 v102, 31, v99
	v_ashrrev_i32_e32 v99, 11, v99
	v_add_u32_e32 v99, v99, v102
	v_mad_i32_i24 v101, v99, s84, v101
	v_cmp_lt_i32_e64 s[0:1], 15, v101
	s_and_saveexec_b64 s[10:11], s[0:1]
	s_xor_b64 s[0:1], exec, s[10:11]
	v_lshlrev_b32_e32 v99, 12, v99
	v_add3_u32 v102, v99, v101, -16
	v_ashrrev_i32_e32 v103, 31, v102
	v_lshlrev_b64 v[102:103], 12, v[102:103]
	v_lshl_add_u64 v[102:103], s[88:89], 0, v[102:103]
	s_andn2_saveexec_b64 s[0:1], s[0:1]
	v_lshlrev_b32_e32 v99, 14, v99
	v_lshl_add_u32 v102, v101, 10, v99
	v_ashrrev_i32_e32 v103, 31, v102
	v_lshl_add_u64 v[102:103], v[102:103], 2, s[16:17]
	s_or_b64 exec, exec, s[0:1]
	v_lshl_add_u64 v[102:103], v[130:131], 2, v[102:103]
	global_load_dword v110, v[102:103], off
	global_load_dword v109, v[102:103], off offset:128
	v_cmp_gt_i32_e64 s[10:11], s85, v100
	s_nop 1
	v_cndmask_b32_e64 v101, v181, v100, s[10:11]
	v_mul_hi_i32 v99, v101, s83
	v_lshrrev_b32_e32 v102, 31, v99
	v_ashrrev_i32_e32 v99, 11, v99
	v_add_u32_e32 v99, v99, v102
	v_mad_i32_i24 v101, v99, s84, v101
	v_cmp_lt_i32_e64 s[0:1], 15, v101
	s_and_saveexec_b64 s[22:23], s[0:1]
	s_xor_b64 s[0:1], exec, s[22:23]
	v_lshlrev_b32_e32 v99, 12, v99
	v_add3_u32 v102, v99, v101, -16
	v_ashrrev_i32_e32 v103, 31, v102
	v_lshlrev_b64 v[102:103], 12, v[102:103]
	v_lshl_add_u64 v[102:103], s[88:89], 0, v[102:103]
	s_andn2_saveexec_b64 s[0:1], s[0:1]
	v_lshlrev_b32_e32 v99, 14, v99
	v_lshl_add_u32 v102, v101, 10, v99
	v_ashrrev_i32_e32 v103, 31, v102
	v_lshl_add_u64 v[102:103], v[102:103], 2, s[16:17]
	s_or_b64 exec, exec, s[0:1]
	v_ashrrev_i32_e32 v101, 31, v100
	v_lshlrev_b64 v[100:101], 11, v[100:101]
	v_lshl_add_u64 v[100:101], s[62:63], 0, v[100:101]
	s_waitcnt vmcnt(31)
	v_add_f32_e32 v0, v50, v0
	v_lshl_add_u64 v[100:101], v[130:131], 1, v[100:101]
	v_lshl_add_u64 v[102:103], v[102:103], 0, v[134:135]
	s_and_saveexec_b64 s[0:1], s[10:11]
	s_cbranch_execz .LBB0_4095
	global_store_dword v[102:103], v0, off
	v_mul_f32_e32 v50, v0, v242
	v_cvt_pk_bf16_f32 v50, v50, s0
	global_store_short v[100:101], v50, off

.Lrt2_f:
	s_waitcnt vmcnt(6)
	v_mov_b32_e32 v135, v208
	s_nop 0
	v_ashrrev_i32_e32 v0, 1, v135
	v_and_b32_e32 v0, 0xffffff80, v0
	v_lshrrev_b32_e32 v130, 3, v135
	v_and_b32_e32 v136, 4, v130
	v_add_u32_e32 v137, s9, v0
	v_or_b32_e32 v134, v137, v136
	v_min_i32_e32 v130, 0x403f, v134
	v_mul_hi_i32 v0, v130, s80
	v_lshrrev_b32_e32 v131, 31, v0
	v_ashrrev_i32_e32 v0, 11, v0
	v_add_u32_e32 v0, v0, v131
	v_mad_i32_i24 v130, v0, s81, v130
	v_cmp_lt_i32_e32 vcc, 15, v130
	s_and_saveexec_b64 s[0:1], vcc
	s_xor_b64 s[0:1], exec, s[0:1]
	v_lshlrev_b32_e32 v0, 12, v0
	v_add3_u32 v130, v0, v130, -16
	v_ashrrev_i32_e32 v131, 31, v130
	v_lshlrev_b64 v[130:131], 12, v[130:131]
	v_lshl_add_u64 v[132:133], s[88:89], 0, v[130:131]
	s_andn2_saveexec_b64 s[0:1], s[0:1]
	v_lshlrev_b32_e32 v0, 14, v0
	v_lshl_add_u32 v130, v130, 10, v0
	v_ashrrev_i32_e32 v131, 31, v130
	v_lshl_add_u64 v[132:133], v[130:131], 2, s[16:17]
	s_or_b64 exec, exec, s[0:1]
	v_bfe_u32 v0, v135, 6, 2
	s_waitcnt vmcnt(2)
	v_and_b32_e32 v138, 31, v135
	v_lshlrev_b32_e32 v130, 6, v0
	v_or3_b32 v130, v130, s8, v138
	v_ashrrev_i32_e32 v131, 31, v130
	v_lshl_add_u64 v[132:133], v[130:131], 2, v[132:133]
	global_load_dword v139, v[132:133], off
	global_load_dword v140, v[132:133], off offset:128
	v_or_b32_e32 v187, 1, v134
	v_min_i32_e32 v132, 0x403f, v187
	v_mul_hi_i32 v133, v132, s80
	v_lshrrev_b32_e32 v141, 31, v133
	v_ashrrev_i32_e32 v133, 11, v133
	v_add_u32_e32 v141, v133, v141
	v_mad_i32_i24 v142, v141, s81, v132
	v_cmp_lt_i32_e32 vcc, 15, v142
	s_and_saveexec_b64 s[0:1], vcc
	s_xor_b64 s[0:1], exec, s[0:1]
	v_lshlrev_b32_e32 v132, 12, v141
	v_add3_u32 v132, v132, v142, -16
	v_ashrrev_i32_e32 v133, 31, v132
	v_lshlrev_b64 v[132:133], 12, v[132:133]
	v_lshl_add_u64 v[132:133], s[88:89], 0, v[132:133]
	s_andn2_saveexec_b64 s[0:1], s[0:1]
	v_lshlrev_b32_e32 v132, 14, v141
	v_lshl_add_u32 v132, v142, 10, v132
	v_ashrrev_i32_e32 v133, 31, v132
	v_lshl_add_u64 v[132:133], v[132:133], 2, s[16:17]
	s_or_b64 exec, exec, s[0:1]
	v_lshl_add_u64 v[132:133], v[130:131], 2, v[132:133]
	global_load_dword v141, v[132:133], off
	global_load_dword v142, v[132:133], off offset:128
	v_or_b32_e32 v186, 2, v134
	v_min_i32_e32 v132, 0x403f, v186
	v_mul_hi_i32 v133, v132, s80
	v_lshrrev_b32_e32 v143, 31, v133
	v_ashrrev_i32_e32 v133, 11, v133
	v_add_u32_e32 v143, v133, v143
	v_mad_i32_i24 v144, v143, s81, v132
	v_cmp_lt_i32_e32 vcc, 15, v144
	s_and_saveexec_b64 s[0:1], vcc
	s_xor_b64 s[0:1], exec, s[0:1]
	v_lshlrev_b32_e32 v132, 12, v143
	v_add3_u32 v132, v132, v144, -16
	v_ashrrev_i32_e32 v133, 31, v132
	v_lshlrev_b64 v[132:133], 12, v[132:133]
	v_lshl_add_u64 v[132:133], s[88:89], 0, v[132:133]
	s_andn2_saveexec_b64 s[0:1], s[0:1]
	v_lshlrev_b32_e32 v132, 14, v143
	v_lshl_add_u32 v132, v144, 10, v132
	v_ashrrev_i32_e32 v133, 31, v132
	v_lshl_add_u64 v[132:133], v[132:133], 2, s[16:17]
	s_or_b64 exec, exec, s[0:1]
	v_lshl_add_u64 v[132:133], v[130:131], 2, v[132:133]
	global_load_dword v143, v[132:133], off
	global_load_dword v144, v[132:133], off offset:128
	v_or_b32_e32 v185, 3, v134
	v_min_i32_e32 v132, 0x403f, v185
	v_mul_hi_i32 v133, v132, s80
	v_lshrrev_b32_e32 v145, 31, v133
	v_ashrrev_i32_e32 v133, 11, v133
	v_add_u32_e32 v145, v133, v145
	s_waitcnt vmcnt(7)
	v_mad_i32_i24 v146, v145, s81, v132
	v_cmp_lt_i32_e32 vcc, 15, v146
	s_and_saveexec_b64 s[0:1], vcc
	s_xor_b64 s[0:1], exec, s[0:1]
	v_lshlrev_b32_e32 v132, 12, v145
	v_add3_u32 v132, v132, v146, -16
	v_ashrrev_i32_e32 v133, 31, v132
	v_lshlrev_b64 v[132:133], 12, v[132:133]
	v_lshl_add_u64 v[132:133], s[88:89], 0, v[132:133]
	s_andn2_saveexec_b64 s[0:1], s[0:1]
	v_lshlrev_b32_e32 v132, 14, v145
	v_lshl_add_u32 v132, v146, 10, v132
	v_ashrrev_i32_e32 v133, 31, v132
	v_lshl_add_u64 v[132:133], v[132:133], 2, s[16:17]
	s_or_b64 exec, exec, s[0:1]
	v_lshl_add_u64 v[132:133], v[130:131], 2, v[132:133]
	global_load_dword v145, v[132:133], off
	global_load_dword v146, v[132:133], off offset:128
	v_or_b32_e32 v184, 8, v134
	v_min_i32_e32 v132, 0x403f, v184
	v_mul_hi_i32 v133, v132, s80
	v_lshrrev_b32_e32 v147, 31, v133
	v_ashrrev_i32_e32 v133, 11, v133
	v_add_u32_e32 v147, v133, v147
	v_mad_i32_i24 v148, v147, s81, v132
	v_cmp_lt_i32_e32 vcc, 15, v148
	s_and_saveexec_b64 s[0:1], vcc
	s_xor_b64 s[0:1], exec, s[0:1]
	v_lshlrev_b32_e32 v132, 12, v147
	v_add3_u32 v132, v132, v148, -16
	v_ashrrev_i32_e32 v133, 31, v132
	v_lshlrev_b64 v[132:133], 12, v[132:133]
	v_lshl_add_u64 v[132:133], s[88:89], 0, v[132:133]
	s_andn2_saveexec_b64 s[0:1], s[0:1]
	v_lshlrev_b32_e32 v132, 14, v147
	v_lshl_add_u32 v132, v148, 10, v132
	v_ashrrev_i32_e32 v133, 31, v132
	v_lshl_add_u64 v[132:133], v[132:133], 2, s[16:17]
	s_or_b64 exec, exec, s[0:1]
	v_lshl_add_u64 v[132:133], v[130:131], 2, v[132:133]
	global_load_dword v147, v[132:133], off
	global_load_dword v148, v[132:133], off offset:128
	v_or_b32_e32 v183, 9, v134
	v_min_i32_e32 v132, 0x403f, v183
	v_mul_hi_i32 v133, v132, s80
	v_lshrrev_b32_e32 v149, 31, v133
	v_ashrrev_i32_e32 v133, 11, v133
	v_add_u32_e32 v149, v133, v149
	v_mad_i32_i24 v150, v149, s81, v132
	v_cmp_lt_i32_e32 vcc, 15, v150
	s_and_saveexec_b64 s[0:1], vcc
	s_xor_b64 s[0:1], exec, s[0:1]
	v_lshlrev_b32_e32 v132, 12, v149
	v_add3_u32 v132, v132, v150, -16
	v_ashrrev_i32_e32 v133, 31, v132
	v_lshlrev_b64 v[132:133], 12, v[132:133]
	v_lshl_add_u64 v[132:133], s[88:89], 0, v[132:133]
	s_andn2_saveexec_b64 s[0:1], s[0:1]
	v_lshlrev_b32_e32 v132, 14, v149
	v_lshl_add_u32 v132, v150, 10, v132
	v_ashrrev_i32_e32 v133, 31, v132
	v_lshl_add_u64 v[132:133], v[132:133], 2, s[16:17]
	s_or_b64 exec, exec, s[0:1]
	v_lshl_add_u64 v[132:133], v[130:131], 2, v[132:133]
	global_load_dword v149, v[132:133], off
	global_load_dword v150, v[132:133], off offset:128
	v_or_b32_e32 v182, 10, v134
	v_min_i32_e32 v132, 0x403f, v182
	v_mul_hi_i32 v133, v132, s80
	v_lshrrev_b32_e32 v151, 31, v133
	v_ashrrev_i32_e32 v133, 11, v133
	v_add_u32_e32 v151, v133, v151
	v_mad_i32_i24 v152, v151, s81, v132
	v_cmp_lt_i32_e32 vcc, 15, v152
	s_and_saveexec_b64 s[0:1], vcc
	s_xor_b64 s[0:1], exec, s[0:1]
	v_lshlrev_b32_e32 v132, 12, v151
	v_add3_u32 v132, v132, v152, -16
	v_ashrrev_i32_e32 v133, 31, v132
	v_lshlrev_b64 v[132:133], 12, v[132:133]
	v_lshl_add_u64 v[132:133], s[88:89], 0, v[132:133]
	s_andn2_saveexec_b64 s[0:1], s[0:1]
	v_lshlrev_b32_e32 v132, 14, v151
	v_lshl_add_u32 v132, v152, 10, v132
	v_ashrrev_i32_e32 v133, 31, v132
	v_lshl_add_u64 v[132:133], v[132:133], 2, s[16:17]
	s_or_b64 exec, exec, s[0:1]
	v_lshl_add_u64 v[132:133], v[130:131], 2, v[132:133]
	global_load_dword v151, v[132:133], off
	global_load_dword v152, v[132:133], off offset:128
	v_or_b32_e32 v181, 11, v134
	v_min_i32_e32 v132, 0x403f, v181
	v_mul_hi_i32 v133, v132, s80
	v_lshrrev_b32_e32 v153, 31, v133
	v_ashrrev_i32_e32 v133, 11, v133
	v_add_u32_e32 v153, v133, v153
	s_waitcnt vmcnt(14)
	v_mad_i32_i24 v154, v153, s81, v132
	v_cmp_lt_i32_e32 vcc, 15, v154
	s_and_saveexec_b64 s[0:1], vcc
	s_xor_b64 s[0:1], exec, s[0:1]
	v_lshlrev_b32_e32 v132, 12, v153
	v_add3_u32 v132, v132, v154, -16
	v_ashrrev_i32_e32 v133, 31, v132
	v_lshlrev_b64 v[132:133], 12, v[132:133]
	v_lshl_add_u64 v[132:133], s[88:89], 0, v[132:133]
	s_andn2_saveexec_b64 s[0:1], s[0:1]
	v_lshlrev_b32_e32 v132, 14, v153
	v_lshl_add_u32 v132, v154, 10, v132
	v_ashrrev_i32_e32 v133, 31, v132
	v_lshl_add_u64 v[132:133], v[132:133], 2, s[16:17]
	s_or_b64 exec, exec, s[0:1]
	v_lshl_add_u64 v[132:133], v[130:131], 2, v[132:133]
	global_load_dword v153, v[132:133], off
	global_load_dword v154, v[132:133], off offset:128
	v_or_b32_e32 v180, 16, v134
	v_min_i32_e32 v132, 0x403f, v180
	v_mul_hi_i32 v133, v132, s80
	v_lshrrev_b32_e32 v155, 31, v133
	v_ashrrev_i32_e32 v133, 11, v133
	v_add_u32_e32 v155, v133, v155
	v_mad_i32_i24 v156, v155, s81, v132
	v_cmp_lt_i32_e32 vcc, 15, v156
	s_and_saveexec_b64 s[0:1], vcc
	s_xor_b64 s[0:1], exec, s[0:1]
	v_lshlrev_b32_e32 v132, 12, v155
	v_add3_u32 v132, v132, v156, -16
	v_ashrrev_i32_e32 v133, 31, v132
	v_lshlrev_b64 v[132:133], 12, v[132:133]
	v_lshl_add_u64 v[132:133], s[88:89], 0, v[132:133]
	s_andn2_saveexec_b64 s[0:1], s[0:1]
	v_lshlrev_b32_e32 v132, 14, v155
	v_lshl_add_u32 v132, v156, 10, v132
	v_ashrrev_i32_e32 v133, 31, v132
	v_lshl_add_u64 v[132:133], v[132:133], 2, s[16:17]
	s_or_b64 exec, exec, s[0:1]
	v_lshl_add_u64 v[132:133], v[130:131], 2, v[132:133]
	global_load_dword v155, v[132:133], off
	global_load_dword v156, v[132:133], off offset:128
	v_or_b32_e32 v177, 17, v134
	v_min_i32_e32 v132, 0x403f, v177
	v_mul_hi_i32 v133, v132, s80
	v_lshrrev_b32_e32 v157, 31, v133
	v_ashrrev_i32_e32 v133, 11, v133
	v_add_u32_e32 v157, v133, v157
	v_mad_i32_i24 v158, v157, s81, v132
	v_cmp_lt_i32_e32 vcc, 15, v158
	s_and_saveexec_b64 s[0:1], vcc
	s_xor_b64 s[0:1], exec, s[0:1]
	v_lshlrev_b32_e32 v132, 12, v157
	v_add3_u32 v132, v132, v158, -16
	v_ashrrev_i32_e32 v133, 31, v132
	v_lshlrev_b64 v[132:133], 12, v[132:133]
	v_lshl_add_u64 v[132:133], s[88:89], 0, v[132:133]
	s_andn2_saveexec_b64 s[0:1], s[0:1]
	v_lshlrev_b32_e32 v132, 14, v157
	v_lshl_add_u32 v132, v158, 10, v132
	v_ashrrev_i32_e32 v133, 31, v132
	v_lshl_add_u64 v[132:133], v[132:133], 2, s[16:17]
	s_or_b64 exec, exec, s[0:1]
	v_lshl_add_u64 v[132:133], v[130:131], 2, v[132:133]
	global_load_dword v157, v[132:133], off
	global_load_dword v158, v[132:133], off offset:128
	v_or_b32_e32 v176, 18, v134
	v_min_i32_e32 v132, 0x403f, v176
	v_mul_hi_i32 v133, v132, s80
	v_lshrrev_b32_e32 v159, 31, v133
	v_ashrrev_i32_e32 v133, 11, v133
	v_add_u32_e32 v159, v133, v159
	v_mad_i32_i24 v160, v159, s81, v132
	v_cmp_lt_i32_e32 vcc, 15, v160
	s_and_saveexec_b64 s[0:1], vcc
	s_xor_b64 s[0:1], exec, s[0:1]
	v_lshlrev_b32_e32 v132, 12, v159
	v_add3_u32 v132, v132, v160, -16
	v_ashrrev_i32_e32 v133, 31, v132
	v_lshlrev_b64 v[132:133], 12, v[132:133]
	v_lshl_add_u64 v[132:133], s[88:89], 0, v[132:133]
	s_andn2_saveexec_b64 s[0:1], s[0:1]
	v_lshlrev_b32_e32 v132, 14, v159
	v_lshl_add_u32 v132, v160, 10, v132
	v_ashrrev_i32_e32 v133, 31, v132
	v_lshl_add_u64 v[132:133], v[132:133], 2, s[16:17]
	s_or_b64 exec, exec, s[0:1]
	v_lshl_add_u64 v[132:133], v[130:131], 2, v[132:133]
	global_load_dword v159, v[132:133], off
	global_load_dword v160, v[132:133], off offset:128
	v_or_b32_e32 v175, 19, v134
	v_min_i32_e32 v132, 0x403f, v175
	v_mul_hi_i32 v133, v132, s80
	v_lshrrev_b32_e32 v161, 31, v133
	v_ashrrev_i32_e32 v133, 11, v133
	v_add_u32_e32 v161, v133, v161
	v_mad_i32_i24 v162, v161, s81, v132
	v_cmp_lt_i32_e32 vcc, 15, v162
	s_and_saveexec_b64 s[0:1], vcc
	s_xor_b64 s[0:1], exec, s[0:1]
	v_lshlrev_b32_e32 v132, 12, v161
	v_add3_u32 v132, v132, v162, -16
	v_ashrrev_i32_e32 v133, 31, v132
	v_lshlrev_b64 v[132:133], 12, v[132:133]
	v_lshl_add_u64 v[132:133], s[88:89], 0, v[132:133]
	s_andn2_saveexec_b64 s[0:1], s[0:1]
	v_lshlrev_b32_e32 v132, 14, v161
	v_lshl_add_u32 v132, v162, 10, v132
	v_ashrrev_i32_e32 v133, 31, v132
	v_lshl_add_u64 v[132:133], v[132:133], 2, s[16:17]
	s_or_b64 exec, exec, s[0:1]
	v_lshl_add_u64 v[132:133], v[130:131], 2, v[132:133]
	global_load_dword v161, v[132:133], off
	global_load_dword v162, v[132:133], off offset:128
	v_or_b32_e32 v174, 24, v134
	v_min_i32_e32 v132, 0x403f, v174
	v_mul_hi_i32 v133, v132, s80
	v_lshrrev_b32_e32 v163, 31, v133
	v_ashrrev_i32_e32 v133, 11, v133
	v_add_u32_e32 v163, v133, v163
	v_mad_i32_i24 v164, v163, s81, v132
	v_cmp_lt_i32_e32 vcc, 15, v164
	s_and_saveexec_b64 s[0:1], vcc
	s_xor_b64 s[0:1], exec, s[0:1]
	v_lshlrev_b32_e32 v132, 12, v163
	v_add3_u32 v132, v132, v164, -16
	v_ashrrev_i32_e32 v133, 31, v132
	v_lshlrev_b64 v[132:133], 12, v[132:133]
	v_lshl_add_u64 v[132:133], s[88:89], 0, v[132:133]
	s_andn2_saveexec_b64 s[0:1], s[0:1]
	v_lshlrev_b32_e32 v132, 14, v163
	v_lshl_add_u32 v132, v164, 10, v132
	v_ashrrev_i32_e32 v133, 31, v132
	v_lshl_add_u64 v[132:133], v[132:133], 2, s[16:17]
	s_or_b64 exec, exec, s[0:1]
	v_lshl_add_u64 v[132:133], v[130:131], 2, v[132:133]
	global_load_dword v163, v[132:133], off
	global_load_dword v164, v[132:133], off offset:128
	v_or_b32_e32 v173, 25, v134
	v_min_i32_e32 v132, 0x403f, v173
	v_mul_hi_i32 v133, v132, s80
	v_lshrrev_b32_e32 v165, 31, v133
	v_ashrrev_i32_e32 v133, 11, v133
	v_add_u32_e32 v165, v133, v165
	v_mad_i32_i24 v166, v165, s81, v132
	v_cmp_lt_i32_e32 vcc, 15, v166
	s_and_saveexec_b64 s[0:1], vcc
	s_xor_b64 s[0:1], exec, s[0:1]
	v_lshlrev_b32_e32 v132, 12, v165
	v_add3_u32 v132, v132, v166, -16
	v_ashrrev_i32_e32 v133, 31, v132
	v_lshlrev_b64 v[132:133], 12, v[132:133]
	v_lshl_add_u64 v[132:133], s[88:89], 0, v[132:133]
	s_andn2_saveexec_b64 s[0:1], s[0:1]
	v_lshlrev_b32_e32 v132, 14, v165
	v_lshl_add_u32 v132, v166, 10, v132
	v_ashrrev_i32_e32 v133, 31, v132
	v_lshl_add_u64 v[132:133], v[132:133], 2, s[16:17]
	s_or_b64 exec, exec, s[0:1]
	v_lshl_add_u64 v[132:133], v[130:131], 2, v[132:133]
	global_load_dword v165, v[132:133], off
	global_load_dword v166, v[132:133], off offset:128
	v_or_b32_e32 v172, 26, v134
	v_min_i32_e32 v132, 0x403f, v172
	v_mul_hi_i32 v133, v132, s80
	v_lshrrev_b32_e32 v167, 31, v133
	v_ashrrev_i32_e32 v133, 11, v133
	v_add_u32_e32 v167, v133, v167
	v_mad_i32_i24 v168, v167, s81, v132
	v_cmp_lt_i32_e32 vcc, 15, v168
	s_and_saveexec_b64 s[0:1], vcc
	s_xor_b64 s[0:1], exec, s[0:1]
	v_lshlrev_b32_e32 v132, 12, v167
	v_add3_u32 v132, v132, v168, -16
	v_ashrrev_i32_e32 v133, 31, v132
	v_lshlrev_b64 v[132:133], 12, v[132:133]
	v_lshl_add_u64 v[132:133], s[88:89], 0, v[132:133]
	s_andn2_saveexec_b64 s[0:1], s[0:1]
	v_lshlrev_b32_e32 v132, 14, v167
	v_lshl_add_u32 v132, v168, 10, v132
	v_ashrrev_i32_e32 v133, 31, v132
	v_lshl_add_u64 v[132:133], v[132:133], 2, s[16:17]
	s_or_b64 exec, exec, s[0:1]
	v_lshl_add_u64 v[132:133], v[130:131], 2, v[132:133]
	global_load_dword v167, v[132:133], off
	global_load_dword v168, v[132:133], off offset:128
	v_or_b32_e32 v171, 27, v134
	v_min_i32_e32 v132, 0x403f, v171
	v_mul_hi_i32 v133, v132, s80
	v_lshrrev_b32_e32 v169, 31, v133
	v_ashrrev_i32_e32 v133, 11, v133
	v_add_u32_e32 v169, v133, v169
	v_mad_i32_i24 v170, v169, s81, v132
	v_cmp_lt_i32_e32 vcc, 15, v170
	s_and_saveexec_b64 s[0:1], vcc
	s_xor_b64 s[0:1], exec, s[0:1]
	v_lshlrev_b32_e32 v132, 12, v169
	v_add3_u32 v132, v132, v170, -16
	v_ashrrev_i32_e32 v133, 31, v132
	v_lshlrev_b64 v[132:133], 12, v[132:133]
	v_lshl_add_u64 v[132:133], s[88:89], 0, v[132:133]
	s_andn2_saveexec_b64 s[0:1], s[0:1]
	v_lshlrev_b32_e32 v132, 14, v169
	v_lshl_add_u32 v132, v170, 10, v132
	v_ashrrev_i32_e32 v133, 31, v132
	v_lshl_add_u64 v[132:133], v[132:133], 2, s[16:17]
	s_or_b64 exec, exec, s[0:1]
	v_lshl_add_u64 v[132:133], v[130:131], 2, v[132:133]
	global_load_dword v169, v[132:133], off
	global_load_dword v170, v[132:133], off offset:128
	v_cmp_gt_i32_e32 vcc, s82, v134
	s_nop 1
	v_cndmask_b32_e32 v132, v179, v134, vcc
	v_mul_hi_i32 v133, v132, s80
	v_lshrrev_b32_e32 v188, 31, v133
	v_ashrrev_i32_e32 v133, 11, v133
	v_add_u32_e32 v188, v133, v188
	v_mad_i32_i24 v189, v188, s81, v132
	v_cmp_lt_i32_e64 s[0:1], 15, v189
	s_and_saveexec_b64 s[2:3], s[0:1]
	s_xor_b64 s[0:1], exec, s[2:3]
	v_lshlrev_b32_e32 v132, 12, v188
	v_add3_u32 v132, v132, v189, -16
	v_ashrrev_i32_e32 v133, 31, v132
	v_lshlrev_b64 v[132:133], 12, v[132:133]
	v_lshl_add_u64 v[132:133], s[88:89], 0, v[132:133]
	s_andn2_saveexec_b64 s[0:1], s[0:1]
	v_lshlrev_b32_e32 v132, 14, v188
	v_lshl_add_u32 v132, v189, 10, v132
	v_ashrrev_i32_e32 v133, 31, v132
	v_lshl_add_u64 v[132:133], v[132:133], 2, s[16:17]
	s_or_b64 exec, exec, s[0:1]
	s_waitcnt vmcnt(31)
	v_fmac_f32_e32 v139, 0.5, v114
	v_lshl_add_u64 v[132:133], v[130:131], 2, v[132:133]
	s_and_saveexec_b64 s[0:1], vcc
	s_cbranch_execz .LBB0_4681
	global_store_dword v[132:133], v139, off

.LBB0_4995:
	s_or_b64 exec, exec, s[0:1]
	v_mul_f32_e32 v80, v105, v105
	v_lshlrev_b32_e32 v66, 1, v138
	v_lshlrev_b32_e32 v72, 1, v135
	v_fmac_f32_e32 v80, v104, v104
	v_and_b32_e32 v66, 32, v66
	v_and_b32_e32 v72, 24, v72
	v_and_b32_e32 v104, 3, v135
	v_or3_b32 v66, v104, v72, v66
	v_and_b32_e32 v104, 64, v200
	v_xor_b32_e32 v72, 16, v200
	v_add_u32_e32 v104, 64, v104
	v_mul_f32_e32 v82, v101, v101
	v_mul_f32_e32 v98, v140, v140
	v_and_b32_e32 v99, 16, v135
	v_cmp_lt_i32_e32 vcc, v72, v104
	v_fmac_f32_e32 v82, v100, v100
	v_fmac_f32_e32 v98, v139, v139
	v_cndmask_b32_e32 v72, v200, v72, vcc
	v_cmp_eq_u32_e32 vcc, 0, v99
	v_lshlrev_b32_e32 v72, 2, v72
	v_mul_f32_e32 v78, v109, v109
	v_cndmask_b32_e32 v99, v98, v82, vcc
	ds_bpermute_b32 v99, v72, v99
	v_mul_f32_e32 v79, v107, v107
	v_mul_f32_e32 v94, v148, v148
	v_mul_f32_e32 v95, v146, v146
	v_mul_f32_e32 v73, v119, v119
	v_mul_f32_e32 v77, v111, v111
	v_fmac_f32_e32 v78, v108, v108
	v_fmac_f32_e32 v79, v106, v106
	v_mul_f32_e32 v89, v158, v158
	v_mul_f32_e32 v93, v150, v150
	v_fmac_f32_e32 v94, v147, v147
	v_fmac_f32_e32 v95, v145, v145
	v_cndmask_b32_e32 v82, v82, v98, vcc
	v_fmac_f32_e32 v73, v118, v118
	v_fmac_f32_e32 v77, v110, v110
	v_fmac_f32_e32 v89, v157, v157
	v_fmac_f32_e32 v93, v149, v149
	s_waitcnt lgkmcnt(0)
	v_add_f32_e32 v82, v82, v99
	v_cndmask_b32_e32 v99, v95, v79, vcc
	v_cndmask_b32_e32 v79, v79, v95, vcc
	v_cndmask_b32_e32 v95, v94, v78, vcc
	v_cndmask_b32_e32 v78, v78, v94, vcc
	ds_bpermute_b32 v94, v72, v95
	v_cndmask_b32_e32 v95, v93, v77, vcc
	v_cndmask_b32_e32 v77, v77, v93, vcc
	v_cndmask_b32_e32 v93, v89, v73, vcc
	ds_bpermute_b32 v93, v72, v93
	v_mul_f32_e32 v71, v121, v121
	v_mul_f32_e32 v88, v160, v160
	v_fmac_f32_e32 v71, v120, v120
	v_fmac_f32_e32 v88, v159, v159
	v_cndmask_b32_e32 v73, v73, v89, vcc
	s_waitcnt lgkmcnt(0)
	v_add_f32_e32 v89, v73, v93
	v_cndmask_b32_e32 v73, v88, v71, vcc
	ds_bpermute_b32 v73, v72, v73
	v_mul_f32_e32 v81, v103, v103
	v_mul_f32_e32 v97, v142, v142
	v_mul_f32_e32 v68, v129, v129
	v_mul_f32_e32 v75, v115, v115
	v_mul_f32_e32 v76, v113, v113
	v_fmac_f32_e32 v81, v102, v102
	v_mul_f32_e32 v85, v166, v166
	v_mul_f32_e32 v91, v154, v154
	v_mul_f32_e32 v92, v152, v152
	v_mul_f32_e32 v96, v144, v144
	v_fmac_f32_e32 v97, v141, v141
	v_fmac_f32_e32 v68, v128, v128
	v_mul_f32_e32 v69, v125, v125
	v_mul_f32_e32 v74, v117, v117
	v_fmac_f32_e32 v75, v114, v114
	v_fmac_f32_e32 v76, v112, v112
	v_mul_f32_e32 v83, v170, v170
	v_fmac_f32_e32 v85, v165, v165
	v_mul_f32_e32 v86, v164, v164
	v_mul_f32_e32 v90, v156, v156
	v_fmac_f32_e32 v91, v153, v153
	v_fmac_f32_e32 v92, v151, v151
	v_fmac_f32_e32 v96, v143, v143
	v_mul_f32_e32 v105, v127, v127
	v_cndmask_b32_e32 v98, v97, v81, vcc
	v_cndmask_b32_e32 v71, v71, v88, vcc
	v_fmac_f32_e32 v69, v124, v124
	v_fmac_f32_e32 v74, v116, v116
	v_fmac_f32_e32 v83, v169, v169
	v_fmac_f32_e32 v86, v163, v163
	v_fmac_f32_e32 v90, v155, v155
	v_fmac_f32_e32 v105, v126, v126
	v_cndmask_b32_e32 v81, v81, v97, vcc
	ds_bpermute_b32 v97, v72, v98
	v_cndmask_b32_e32 v98, v96, v80, vcc
	v_cndmask_b32_e32 v80, v80, v96, vcc
	v_cndmask_b32_e32 v96, v92, v76, vcc
	v_cndmask_b32_e32 v76, v76, v92, vcc
	v_cndmask_b32_e32 v92, v91, v75, vcc
	s_waitcnt lgkmcnt(1)
	v_add_f32_e32 v71, v71, v73
	v_cndmask_b32_e32 v73, v85, v68, vcc
	v_cndmask_b32_e32 v75, v75, v91, vcc
	ds_bpermute_b32 v91, v72, v92
	v_cndmask_b32_e32 v92, v90, v74, vcc
	v_cndmask_b32_e32 v74, v74, v90, vcc
	v_cndmask_b32_e32 v90, v86, v69, vcc
	v_cndmask_b32_e32 v69, v69, v86, vcc
	ds_bpermute_b32 v73, v72, v73
	v_cndmask_b32_e32 v86, v83, v105, vcc
	ds_bpermute_b32 v86, v72, v86
	ds_bpermute_b32 v92, v72, v92
	v_cndmask_b32_e32 v68, v68, v85, vcc
	s_lshl_b32 s0, s4, 2
	s_waitcnt lgkmcnt(2)
	v_add_f32_e32 v68, v68, v73
	v_cndmask_b32_e32 v73, v105, v83, vcc
	s_ashr_i32 s1, s0, 31
	s_waitcnt lgkmcnt(1)
	v_add_f32_e32 v83, v73, v86
	v_xor_b32_e32 v73, 8, v200
	v_mul_f32_e32 v67, v133, v133
	v_mul_f32_e32 v70, v123, v123
	v_mul_f32_e32 v84, v168, v168
	v_mul_f32_e32 v87, v162, v162
	v_and_b32_e32 v100, 8, v135
	s_lshl_b64 s[8:9], s[0:1], 2
	v_cmp_lt_i32_e64 s[0:1], v73, v104
	v_fmac_f32_e32 v67, v132, v132
	v_fmac_f32_e32 v70, v122, v122
	v_fmac_f32_e32 v84, v167, v167
	v_fmac_f32_e32 v87, v161, v161
	s_waitcnt lgkmcnt(0)
	v_add_f32_e32 v74, v74, v92
	v_cndmask_b32_e64 v73, v200, v73, s[0:1]
	v_cmp_eq_u32_e64 s[2:3], 0, v100
	v_add_f32_e32 v81, v81, v97
	v_cndmask_b32_e32 v88, v87, v70, vcc
	v_cndmask_b32_e32 v85, v84, v67, vcc
	v_cndmask_b32_e32 v67, v67, v84, vcc
	v_lshlrev_b32_e32 v73, 2, v73
	v_cndmask_b32_e64 v84, v82, v74, s[2:3]
	ds_bpermute_b32 v99, v72, v99
	ds_bpermute_b32 v88, v72, v88
	v_cndmask_b32_e64 v74, v74, v82, s[2:3]
	ds_bpermute_b32 v82, v73, v84
	v_cndmask_b32_e64 v84, v81, v89, s[2:3]
	ds_bpermute_b32 v84, v73, v84
	ds_bpermute_b32 v90, v72, v90
	v_cndmask_b32_e32 v70, v70, v87, vcc
	s_waitcnt lgkmcnt(4)
	v_add_f32_e32 v79, v79, v99
	s_waitcnt lgkmcnt(3)
	v_add_f32_e32 v70, v70, v88
	s_waitcnt lgkmcnt(2)
	v_add_f32_e32 v82, v74, v82
	v_cndmask_b32_e64 v74, v89, v81, s[2:3]
	ds_bpermute_b32 v96, v72, v96
	ds_bpermute_b32 v85, v72, v85
	s_waitcnt lgkmcnt(3)
	v_add_f32_e32 v81, v74, v84
	v_cndmask_b32_e64 v74, v79, v70, s[2:3]
	ds_bpermute_b32 v74, v73, v74
	ds_bpermute_b32 v98, v72, v98
	ds_bpermute_b32 v95, v72, v95
	v_add_f32_e32 v78, v78, v94
	s_waitcnt lgkmcnt(5)
	v_add_f32_e32 v69, v69, v90
	v_cndmask_b32_e64 v70, v70, v79, s[2:3]
	v_cndmask_b32_e64 v79, v78, v69, s[2:3]
	s_waitcnt lgkmcnt(4)
	v_add_f32_e32 v76, v76, v96
	s_waitcnt lgkmcnt(3)
	v_add_f32_e32 v67, v67, v85
	ds_bpermute_b32 v79, v73, v79
	v_add_f32_e32 v75, v75, v91
	s_waitcnt lgkmcnt(3)
	v_add_f32_e32 v70, v70, v74
	v_cndmask_b32_e64 v74, v76, v67, s[2:3]
	s_waitcnt lgkmcnt(2)
	v_add_f32_e32 v80, v80, v98
	s_waitcnt lgkmcnt(1)
	v_add_f32_e32 v77, v77, v95
	v_cndmask_b32_e64 v67, v67, v76, s[2:3]
	ds_bpermute_b32 v76, v73, v74
	v_cndmask_b32_e64 v74, v75, v83, s[2:3]
	v_cndmask_b32_e64 v85, v80, v71, s[2:3]
	v_cndmask_b32_e64 v71, v71, v80, s[2:3]
	v_cndmask_b32_e64 v80, v77, v68, s[2:3]
	v_cndmask_b32_e64 v68, v68, v77, s[2:3]
	ds_bpermute_b32 v77, v73, v74
	v_xor_b32_e32 v74, 4, v200
	v_and_b32_e32 v101, 4, v135
	v_cndmask_b32_e64 v69, v69, v78, s[2:3]
	v_cmp_lt_i32_e64 s[0:1], v74, v104
	s_waitcnt lgkmcnt(2)
	v_add_f32_e32 v69, v69, v79
	v_cmp_eq_u32_e64 s[4:5], 0, v101
	v_cndmask_b32_e64 v74, v200, v74, s[0:1]
	ds_bpermute_b32 v85, v73, v85
	ds_bpermute_b32 v80, v73, v80
	v_lshlrev_b32_e32 v74, 2, v74
	v_cndmask_b32_e64 v78, v82, v69, s[4:5]
	ds_bpermute_b32 v78, v74, v78
	v_cndmask_b32_e64 v75, v83, v75, s[2:3]
	s_waitcnt lgkmcnt(2)
	v_add_f32_e32 v71, v71, v85
	s_waitcnt lgkmcnt(1)
	v_add_f32_e32 v68, v68, v80
	v_add_f32_e32 v67, v67, v76
	v_add_f32_e32 v75, v75, v77
	v_cndmask_b32_e64 v69, v69, v82, s[4:5]
	s_waitcnt lgkmcnt(0)
	v_add_f32_e32 v69, v69, v78
	v_cndmask_b32_e64 v76, v81, v68, s[4:5]
	v_cndmask_b32_e64 v77, v71, v67, s[4:5]
	v_cndmask_b32_e64 v78, v70, v75, s[4:5]
	ds_bpermute_b32 v76, v74, v76
	ds_bpermute_b32 v77, v74, v77
	ds_bpermute_b32 v78, v74, v78
	v_cndmask_b32_e64 v67, v67, v71, s[4:5]
	v_xor_b32_e32 v71, 2, v200
	v_and_b32_e32 v102, 2, v135
	v_cndmask_b32_e64 v68, v68, v81, s[4:5]
	v_cndmask_b32_e64 v70, v75, v70, s[4:5]
	v_cmp_lt_i32_e64 s[0:1], v71, v104
	s_waitcnt lgkmcnt(2)
	v_add_f32_e32 v68, v68, v76
	s_waitcnt lgkmcnt(1)
	v_add_f32_e32 v67, v67, v77
	s_waitcnt lgkmcnt(0)
	v_add_f32_e32 v70, v70, v78
	v_cndmask_b32_e64 v71, v200, v71, s[0:1]
	v_cmp_eq_u32_e64 s[6:7], 0, v102
	v_lshlrev_b32_e32 v75, 2, v71
	v_and_b32_e32 v103, 1, v135
	v_cndmask_b32_e64 v71, v69, v67, s[6:7]
	v_cndmask_b32_e64 v76, v68, v70, s[6:7]
	ds_bpermute_b32 v71, v75, v71
	ds_bpermute_b32 v76, v75, v76
	v_cndmask_b32_e64 v67, v67, v69, s[6:7]
	v_xor_b32_e32 v69, 1, v200
	s_add_u32 s10, s12, s8
	v_cndmask_b32_e64 v68, v70, v68, s[6:7]
	v_cmp_lt_i32_e64 s[0:1], v69, v104
	s_addc_u32 s11, s13, s9
	s_waitcnt lgkmcnt(1)
	v_add_f32_e32 v67, v67, v71
	s_waitcnt lgkmcnt(0)
	v_add_f32_e32 v70, v68, v76
	v_cmp_eq_u32_e64 s[8:9], 0, v103
	v_cndmask_b32_e64 v69, v200, v69, s[0:1]
	v_lshlrev_b32_e32 v76, 2, v69
	v_cndmask_b32_e64 v68, v67, v70, s[8:9]
	ds_bpermute_b32 v71, v76, v68
	v_or3_b32 v66, v66, v136, v137
	v_lshlrev_b32_e32 v0, 2, v0
	v_lshl_add_u64 v[68:69], s[10:11], 0, v[0:1]
	v_cndmask_b32_e64 v0, v70, v67, s[8:9]
	v_ashrrev_i32_e32 v67, 31, v66
	s_waitcnt lgkmcnt(0)
	v_add_f32_e32 v0, v0, v71
	v_lshlrev_b64 v[70:71], 6, v[66:67]
	v_or_b32_e32 v122, 64, v134
	v_lshl_add_u64 v[70:71], v[68:69], 0, v[70:71]
	v_min_i32_e32 v67, 0x403f, v122
	global_store_dword v[70:71], v0, off
	s_cmp_lg_u32 s32, 0
	s_cbranch_scc0 .Lrt2_c
	s_branch .LBB0_4548
.Lrt2_c:
	v_mul_hi_i32 v0, v67, s80
	v_lshrrev_b32_e32 v70, 31, v0
	v_ashrrev_i32_e32 v0, 11, v0
	v_add_u32_e32 v0, v0, v70
	v_mad_i32_i24 v67, v0, s81, v67
	v_cmp_lt_i32_e64 s[0:1], 15, v67
	s_and_saveexec_b64 s[10:11], s[0:1]
	s_xor_b64 s[0:1], exec, s[10:11]
	v_lshlrev_b32_e32 v0, 12, v0
	v_add3_u32 v70, v0, v67, -16
	v_ashrrev_i32_e32 v71, 31, v70
	v_lshlrev_b64 v[70:71], 12, v[70:71]
	v_lshl_add_u64 v[70:71], s[88:89], 0, v[70:71]
	s_andn2_saveexec_b64 s[0:1], s[0:1]
	v_lshlrev_b32_e32 v0, 14, v0
	v_lshl_add_u32 v70, v67, 10, v0
	v_ashrrev_i32_e32 v71, 31, v70
	v_lshl_add_u64 v[70:71], v[70:71], 2, s[16:17]
	s_or_b64 exec, exec, s[0:1]
	v_lshl_add_u64 v[70:71], v[130:131], 2, v[70:71]
	global_load_dword v0, v[70:71], off
	global_load_dword v67, v[70:71], off offset:128
	v_or_b32_e32 v121, 0x41, v134
	v_min_i32_e32 v70, 0x403f, v121
	v_mul_hi_i32 v71, v70, s80
	v_lshrrev_b32_e32 v77, 31, v71
	v_ashrrev_i32_e32 v71, 11, v71
	v_add_u32_e32 v77, v71, v77
	v_mad_i32_i24 v78, v77, s81, v70
	v_cmp_lt_i32_e64 s[0:1], 15, v78
	s_and_saveexec_b64 s[10:11], s[0:1]
	s_xor_b64 s[0:1], exec, s[10:11]
	v_lshlrev_b32_e32 v70, 12, v77
	v_add3_u32 v70, v70, v78, -16
	v_ashrrev_i32_e32 v71, 31, v70
	v_lshlrev_b64 v[70:71], 12, v[70:71]
	v_lshl_add_u64 v[70:71], s[88:89], 0, v[70:71]
	s_andn2_saveexec_b64 s[0:1], s[0:1]
	v_lshlrev_b32_e32 v70, 14, v77
	v_lshl_add_u32 v70, v78, 10, v70
	v_ashrrev_i32_e32 v71, 31, v70
	v_lshl_add_u64 v[70:71], v[70:71], 2, s[16:17]
	s_or_b64 exec, exec, s[0:1]
	v_lshl_add_u64 v[70:71], v[130:131], 2, v[70:71]
	global_load_dword v77, v[70:71], off
	global_load_dword v78, v[70:71], off offset:128
	v_or_b32_e32 v120, 0x42, v134
	v_min_i32_e32 v70, 0x403f, v120
	v_mul_hi_i32 v71, v70, s80
	v_lshrrev_b32_e32 v79, 31, v71
	v_ashrrev_i32_e32 v71, 11, v71
	v_add_u32_e32 v79, v71, v79
	v_mad_i32_i24 v80, v79, s81, v70
	v_cmp_lt_i32_e64 s[0:1], 15, v80
	s_and_saveexec_b64 s[10:11], s[0:1]
	s_xor_b64 s[0:1], exec, s[10:11]
	v_lshlrev_b32_e32 v70, 12, v79
	v_add3_u32 v70, v70, v80, -16
	v_ashrrev_i32_e32 v71, 31, v70
	v_lshlrev_b64 v[70:71], 12, v[70:71]
	v_lshl_add_u64 v[70:71], s[88:89], 0, v[70:71]
	s_andn2_saveexec_b64 s[0:1], s[0:1]
	v_lshlrev_b32_e32 v70, 14, v79
	v_lshl_add_u32 v70, v80, 10, v70
	v_ashrrev_i32_e32 v71, 31, v70
	v_lshl_add_u64 v[70:71], v[70:71], 2, s[16:17]
	s_or_b64 exec, exec, s[0:1]
	v_lshl_add_u64 v[70:71], v[130:131], 2, v[70:71]
	global_load_dword v79, v[70:71], off
	global_load_dword v80, v[70:71], off offset:128
	v_or_b32_e32 v119, 0x43, v134
	v_min_i32_e32 v70, 0x403f, v119
	v_mul_hi_i32 v71, v70, s80
	v_lshrrev_b32_e32 v81, 31, v71
	v_ashrrev_i32_e32 v71, 11, v71
	v_add_u32_e32 v81, v71, v81
	v_mad_i32_i24 v82, v81, s81, v70
	v_cmp_lt_i32_e64 s[0:1], 15, v82
	s_and_saveexec_b64 s[10:11], s[0:1]
	s_xor_b64 s[0:1], exec, s[10:11]
	v_lshlrev_b32_e32 v70, 12, v81
	v_add3_u32 v70, v70, v82, -16
	v_ashrrev_i32_e32 v71, 31, v70
	v_lshlrev_b64 v[70:71], 12, v[70:71]
	v_lshl_add_u64 v[70:71], s[88:89], 0, v[70:71]
	s_andn2_saveexec_b64 s[0:1], s[0:1]
	v_lshlrev_b32_e32 v70, 14, v81
	v_lshl_add_u32 v70, v82, 10, v70
	v_ashrrev_i32_e32 v71, 31, v70
	v_lshl_add_u64 v[70:71], v[70:71], 2, s[16:17]
	s_or_b64 exec, exec, s[0:1]
	v_lshl_add_u64 v[70:71], v[130:131], 2, v[70:71]
	global_load_dword v81, v[70:71], off
	global_load_dword v82, v[70:71], off offset:128
	v_or_b32_e32 v118, 0x48, v134
	v_min_i32_e32 v70, 0x403f, v118
	v_mul_hi_i32 v71, v70, s80
	v_lshrrev_b32_e32 v83, 31, v71
	v_ashrrev_i32_e32 v71, 11, v71
	v_add_u32_e32 v83, v71, v83
	v_mad_i32_i24 v84, v83, s81, v70
	v_cmp_lt_i32_e64 s[0:1], 15, v84
	s_and_saveexec_b64 s[10:11], s[0:1]
	s_xor_b64 s[0:1], exec, s[10:11]
	v_lshlrev_b32_e32 v70, 12, v83
	v_add3_u32 v70, v70, v84, -16
	v_ashrrev_i32_e32 v71, 31, v70
	v_lshlrev_b64 v[70:71], 12, v[70:71]
	v_lshl_add_u64 v[70:71], s[88:89], 0, v[70:71]
	s_andn2_saveexec_b64 s[0:1], s[0:1]
	v_lshlrev_b32_e32 v70, 14, v83
	v_lshl_add_u32 v70, v84, 10, v70
	v_ashrrev_i32_e32 v71, 31, v70
	v_lshl_add_u64 v[70:71], v[70:71], 2, s[16:17]
	s_or_b64 exec, exec, s[0:1]
	v_lshl_add_u64 v[70:71], v[130:131], 2, v[70:71]
	global_load_dword v83, v[70:71], off
	global_load_dword v84, v[70:71], off offset:128
	v_or_b32_e32 v117, 0x49, v134
	v_min_i32_e32 v70, 0x403f, v117
	v_mul_hi_i32 v71, v70, s80
	v_lshrrev_b32_e32 v85, 31, v71
	v_ashrrev_i32_e32 v71, 11, v71
	v_add_u32_e32 v85, v71, v85
	v_mad_i32_i24 v86, v85, s81, v70
	v_cmp_lt_i32_e64 s[0:1], 15, v86
	s_and_saveexec_b64 s[10:11], s[0:1]
	s_xor_b64 s[0:1], exec, s[10:11]
	v_lshlrev_b32_e32 v70, 12, v85
	v_add3_u32 v70, v70, v86, -16
	v_ashrrev_i32_e32 v71, 31, v70
	v_lshlrev_b64 v[70:71], 12, v[70:71]
	v_lshl_add_u64 v[70:71], s[88:89], 0, v[70:71]
	s_andn2_saveexec_b64 s[0:1], s[0:1]
	v_lshlrev_b32_e32 v70, 14, v85
	v_lshl_add_u32 v70, v86, 10, v70
	v_ashrrev_i32_e32 v71, 31, v70
	v_lshl_add_u64 v[70:71], v[70:71], 2, s[16:17]
	s_or_b64 exec, exec, s[0:1]
	v_lshl_add_u64 v[70:71], v[130:131], 2, v[70:71]
	global_load_dword v85, v[70:71], off
	global_load_dword v86, v[70:71], off offset:128
	v_or_b32_e32 v116, 0x4a, v134
	v_min_i32_e32 v70, 0x403f, v116
	v_mul_hi_i32 v71, v70, s80
	v_lshrrev_b32_e32 v87, 31, v71
	v_ashrrev_i32_e32 v71, 11, v71
	v_add_u32_e32 v87, v71, v87
	v_mad_i32_i24 v88, v87, s81, v70
	v_cmp_lt_i32_e64 s[0:1], 15, v88
	s_and_saveexec_b64 s[10:11], s[0:1]
	s_xor_b64 s[0:1], exec, s[10:11]
	v_lshlrev_b32_e32 v70, 12, v87
	v_add3_u32 v70, v70, v88, -16
	v_ashrrev_i32_e32 v71, 31, v70
	v_lshlrev_b64 v[70:71], 12, v[70:71]
	v_lshl_add_u64 v[70:71], s[88:89], 0, v[70:71]
	s_andn2_saveexec_b64 s[0:1], s[0:1]
	v_lshlrev_b32_e32 v70, 14, v87
	v_lshl_add_u32 v70, v88, 10, v70
	v_ashrrev_i32_e32 v71, 31, v70
	v_lshl_add_u64 v[70:71], v[70:71], 2, s[16:17]
	s_or_b64 exec, exec, s[0:1]
	v_lshl_add_u64 v[70:71], v[130:131], 2, v[70:71]
	global_load_dword v87, v[70:71], off
	global_load_dword v88, v[70:71], off offset:128
	v_or_b32_e32 v115, 0x4b, v134
	v_min_i32_e32 v70, 0x403f, v115
	v_mul_hi_i32 v71, v70, s80
	v_lshrrev_b32_e32 v89, 31, v71
	v_ashrrev_i32_e32 v71, 11, v71
	v_add_u32_e32 v89, v71, v89
	v_mad_i32_i24 v90, v89, s81, v70
	v_cmp_lt_i32_e64 s[0:1], 15, v90
	s_and_saveexec_b64 s[10:11], s[0:1]
	s_xor_b64 s[0:1], exec, s[10:11]
	v_lshlrev_b32_e32 v70, 12, v89
	v_add3_u32 v70, v70, v90, -16
	v_ashrrev_i32_e32 v71, 31, v70
	v_lshlrev_b64 v[70:71], 12, v[70:71]
	v_lshl_add_u64 v[70:71], s[88:89], 0, v[70:71]
	s_andn2_saveexec_b64 s[0:1], s[0:1]
	v_lshlrev_b32_e32 v70, 14, v89
	v_lshl_add_u32 v70, v90, 10, v70
	v_ashrrev_i32_e32 v71, 31, v70
	v_lshl_add_u64 v[70:71], v[70:71], 2, s[16:17]
	s_or_b64 exec, exec, s[0:1]
	v_lshl_add_u64 v[70:71], v[130:131], 2, v[70:71]
	global_load_dword v89, v[70:71], off
	global_load_dword v90, v[70:71], off offset:128
	v_or_b32_e32 v114, 0x50, v134
	v_min_i32_e32 v70, 0x403f, v114
	v_mul_hi_i32 v71, v70, s80
	v_lshrrev_b32_e32 v91, 31, v71
	v_ashrrev_i32_e32 v71, 11, v71
	v_add_u32_e32 v91, v71, v91
	v_mad_i32_i24 v92, v91, s81, v70
	v_cmp_lt_i32_e64 s[0:1], 15, v92
	s_and_saveexec_b64 s[10:11], s[0:1]
	s_xor_b64 s[0:1], exec, s[10:11]
	v_lshlrev_b32_e32 v70, 12, v91
	v_add3_u32 v70, v70, v92, -16
	v_ashrrev_i32_e32 v71, 31, v70
	v_lshlrev_b64 v[70:71], 12, v[70:71]
	v_lshl_add_u64 v[70:71], s[88:89], 0, v[70:71]
	s_andn2_saveexec_b64 s[0:1], s[0:1]
	v_lshlrev_b32_e32 v70, 14, v91
	v_lshl_add_u32 v70, v92, 10, v70
	v_ashrrev_i32_e32 v71, 31, v70
	v_lshl_add_u64 v[70:71], v[70:71], 2, s[16:17]
	s_or_b64 exec, exec, s[0:1]
	v_lshl_add_u64 v[70:71], v[130:131], 2, v[70:71]
	global_load_dword v91, v[70:71], off
	global_load_dword v92, v[70:71], off offset:128
	v_or_b32_e32 v113, 0x51, v134
	v_min_i32_e32 v70, 0x403f, v113
	v_mul_hi_i32 v71, v70, s80
	v_lshrrev_b32_e32 v93, 31, v71
	v_ashrrev_i32_e32 v71, 11, v71
	v_add_u32_e32 v93, v71, v93
	v_mad_i32_i24 v94, v93, s81, v70
	v_cmp_lt_i32_e64 s[0:1], 15, v94
	s_and_saveexec_b64 s[10:11], s[0:1]
	s_xor_b64 s[0:1], exec, s[10:11]
	v_lshlrev_b32_e32 v70, 12, v93
	v_add3_u32 v70, v70, v94, -16
	v_ashrrev_i32_e32 v71, 31, v70
	v_lshlrev_b64 v[70:71], 12, v[70:71]
	v_lshl_add_u64 v[70:71], s[88:89], 0, v[70:71]
	s_andn2_saveexec_b64 s[0:1], s[0:1]
	v_lshlrev_b32_e32 v70, 14, v93
	v_lshl_add_u32 v70, v94, 10, v70
	v_ashrrev_i32_e32 v71, 31, v70
	v_lshl_add_u64 v[70:71], v[70:71], 2, s[16:17]
	s_or_b64 exec, exec, s[0:1]
	v_lshl_add_u64 v[70:71], v[130:131], 2, v[70:71]
	global_load_dword v93, v[70:71], off
	global_load_dword v94, v[70:71], off offset:128
	v_or_b32_e32 v112, 0x52, v134
	v_min_i32_e32 v70, 0x403f, v112
	v_mul_hi_i32 v71, v70, s80
	v_lshrrev_b32_e32 v95, 31, v71
	v_ashrrev_i32_e32 v71, 11, v71
	v_add_u32_e32 v95, v71, v95
	v_mad_i32_i24 v96, v95, s81, v70
	v_cmp_lt_i32_e64 s[0:1], 15, v96
	s_and_saveexec_b64 s[10:11], s[0:1]
	s_xor_b64 s[0:1], exec, s[10:11]
	v_lshlrev_b32_e32 v70, 12, v95
	v_add3_u32 v70, v70, v96, -16
	v_ashrrev_i32_e32 v71, 31, v70
	v_lshlrev_b64 v[70:71], 12, v[70:71]
	v_lshl_add_u64 v[70:71], s[88:89], 0, v[70:71]
	s_andn2_saveexec_b64 s[0:1], s[0:1]
	v_lshlrev_b32_e32 v70, 14, v95
	v_lshl_add_u32 v70, v96, 10, v70
	v_ashrrev_i32_e32 v71, 31, v70
	v_lshl_add_u64 v[70:71], v[70:71], 2, s[16:17]
	s_or_b64 exec, exec, s[0:1]
	v_lshl_add_u64 v[70:71], v[130:131], 2, v[70:71]
	global_load_dword v95, v[70:71], off
	global_load_dword v96, v[70:71], off offset:128
	v_or_b32_e32 v111, 0x53, v134
	v_min_i32_e32 v70, 0x403f, v111
	v_mul_hi_i32 v71, v70, s80
	v_lshrrev_b32_e32 v97, 31, v71
	v_ashrrev_i32_e32 v71, 11, v71
	v_add_u32_e32 v97, v71, v97
	v_mad_i32_i24 v98, v97, s81, v70
	v_cmp_lt_i32_e64 s[0:1], 15, v98
	s_and_saveexec_b64 s[10:11], s[0:1]
	s_xor_b64 s[0:1], exec, s[10:11]
	v_lshlrev_b32_e32 v70, 12, v97
	v_add3_u32 v70, v70, v98, -16
	v_ashrrev_i32_e32 v71, 31, v70
	v_lshlrev_b64 v[70:71], 12, v[70:71]
	v_lshl_add_u64 v[70:71], s[88:89], 0, v[70:71]
	s_andn2_saveexec_b64 s[0:1], s[0:1]
	v_lshlrev_b32_e32 v70, 14, v97
	v_lshl_add_u32 v70, v98, 10, v70
	v_ashrrev_i32_e32 v71, 31, v70
	v_lshl_add_u64 v[70:71], v[70:71], 2, s[16:17]
	s_or_b64 exec, exec, s[0:1]
	v_lshl_add_u64 v[70:71], v[130:131], 2, v[70:71]
	global_load_dword v97, v[70:71], off
	global_load_dword v98, v[70:71], off offset:128
	v_or_b32_e32 v110, 0x58, v134
	v_min_i32_e32 v70, 0x403f, v110
	v_mul_hi_i32 v71, v70, s80
	v_lshrrev_b32_e32 v99, 31, v71
	v_ashrrev_i32_e32 v71, 11, v71
	v_add_u32_e32 v99, v71, v99
	v_mad_i32_i24 v100, v99, s81, v70
	v_cmp_lt_i32_e64 s[0:1], 15, v100
	s_and_saveexec_b64 s[10:11], s[0:1]
	s_xor_b64 s[0:1], exec, s[10:11]
	v_lshlrev_b32_e32 v70, 12, v99
	v_add3_u32 v70, v70, v100, -16
	v_ashrrev_i32_e32 v71, 31, v70
	v_lshlrev_b64 v[70:71], 12, v[70:71]
	v_lshl_add_u64 v[70:71], s[88:89], 0, v[70:71]
	s_andn2_saveexec_b64 s[0:1], s[0:1]
	v_lshlrev_b32_e32 v70, 14, v99
	v_lshl_add_u32 v70, v100, 10, v70
	v_ashrrev_i32_e32 v71, 31, v70
	v_lshl_add_u64 v[70:71], v[70:71], 2, s[16:17]
	s_or_b64 exec, exec, s[0:1]
	v_lshl_add_u64 v[70:71], v[130:131], 2, v[70:71]
	global_load_dword v99, v[70:71], off
	global_load_dword v100, v[70:71], off offset:128
	v_or_b32_e32 v109, 0x59, v134
	v_min_i32_e32 v70, 0x403f, v109
	v_mul_hi_i32 v71, v70, s80
	v_lshrrev_b32_e32 v101, 31, v71
	v_ashrrev_i32_e32 v71, 11, v71
	v_add_u32_e32 v101, v71, v101
	v_mad_i32_i24 v102, v101, s81, v70
	v_cmp_lt_i32_e64 s[0:1], 15, v102
	s_and_saveexec_b64 s[10:11], s[0:1]
	s_xor_b64 s[0:1], exec, s[10:11]
	v_lshlrev_b32_e32 v70, 12, v101
	v_add3_u32 v70, v70, v102, -16
	v_ashrrev_i32_e32 v71, 31, v70
	v_lshlrev_b64 v[70:71], 12, v[70:71]
	v_lshl_add_u64 v[70:71], s[88:89], 0, v[70:71]
	s_andn2_saveexec_b64 s[0:1], s[0:1]
	v_lshlrev_b32_e32 v70, 14, v101
	v_lshl_add_u32 v70, v102, 10, v70
	v_ashrrev_i32_e32 v71, 31, v70
	v_lshl_add_u64 v[70:71], v[70:71], 2, s[16:17]
	s_or_b64 exec, exec, s[0:1]
	v_lshl_add_u64 v[70:71], v[130:131], 2, v[70:71]
	global_load_dword v101, v[70:71], off
	global_load_dword v102, v[70:71], off offset:128
	v_or_b32_e32 v108, 0x5a, v134
	v_min_i32_e32 v70, 0x403f, v108
	v_mul_hi_i32 v71, v70, s80
	v_lshrrev_b32_e32 v103, 31, v71
	v_ashrrev_i32_e32 v71, 11, v71
	v_add_u32_e32 v103, v71, v103
	v_mad_i32_i24 v104, v103, s81, v70
	v_cmp_lt_i32_e64 s[0:1], 15, v104
	s_and_saveexec_b64 s[10:11], s[0:1]
	s_xor_b64 s[0:1], exec, s[10:11]
	v_lshlrev_b32_e32 v70, 12, v103
	v_add3_u32 v70, v70, v104, -16
	v_ashrrev_i32_e32 v71, 31, v70
	v_lshlrev_b64 v[70:71], 12, v[70:71]
	v_lshl_add_u64 v[70:71], s[88:89], 0, v[70:71]
	s_andn2_saveexec_b64 s[0:1], s[0:1]
	v_lshlrev_b32_e32 v70, 14, v103
	v_lshl_add_u32 v70, v104, 10, v70
	v_ashrrev_i32_e32 v71, 31, v70
	v_lshl_add_u64 v[70:71], v[70:71], 2, s[16:17]
	s_or_b64 exec, exec, s[0:1]
	v_lshl_add_u64 v[70:71], v[130:131], 2, v[70:71]
	global_load_dword v103, v[70:71], off
	global_load_dword v104, v[70:71], off offset:128
	v_or_b32_e32 v107, 0x5b, v134
	v_min_i32_e32 v70, 0x403f, v107
	v_mul_hi_i32 v71, v70, s80
	v_lshrrev_b32_e32 v105, 31, v71
	v_ashrrev_i32_e32 v71, 11, v71
	v_add_u32_e32 v105, v71, v105
	v_mad_i32_i24 v106, v105, s81, v70
	v_cmp_lt_i32_e64 s[0:1], 15, v106
	s_and_saveexec_b64 s[10:11], s[0:1]
	s_xor_b64 s[0:1], exec, s[10:11]
	v_lshlrev_b32_e32 v70, 12, v105
	v_add3_u32 v70, v70, v106, -16
	v_ashrrev_i32_e32 v71, 31, v70
	v_lshlrev_b64 v[70:71], 12, v[70:71]
	v_lshl_add_u64 v[70:71], s[88:89], 0, v[70:71]
	s_andn2_saveexec_b64 s[0:1], s[0:1]
	v_lshlrev_b32_e32 v70, 14, v105
	v_lshl_add_u32 v70, v106, 10, v70
	v_ashrrev_i32_e32 v71, 31, v70
	v_lshl_add_u64 v[70:71], v[70:71], 2, s[16:17]
	s_or_b64 exec, exec, s[0:1]
	v_lshl_add_u64 v[70:71], v[130:131], 2, v[70:71]
	global_load_dword v105, v[70:71], off
	global_load_dword v106, v[70:71], off offset:128
	v_cmp_gt_i32_e64 s[10:11], s82, v122
	s_nop 1
	v_cndmask_b32_e64 v70, v179, v122, s[10:11]
	v_mul_hi_i32 v71, v70, s80
	v_lshrrev_b32_e32 v122, 31, v71
	v_ashrrev_i32_e32 v71, 11, v71
	v_add_u32_e32 v122, v71, v122
	v_mad_i32_i24 v123, v122, s81, v70
	v_cmp_lt_i32_e64 s[0:1], 15, v123
	s_and_saveexec_b64 s[54:55], s[0:1]
	s_xor_b64 s[0:1], exec, s[54:55]
	v_lshlrev_b32_e32 v70, 12, v122
	v_add3_u32 v70, v70, v123, -16
	v_ashrrev_i32_e32 v71, 31, v70
	v_lshlrev_b64 v[70:71], 12, v[70:71]
	v_lshl_add_u64 v[70:71], s[88:89], 0, v[70:71]
	s_andn2_saveexec_b64 s[0:1], s[0:1]
	v_lshlrev_b32_e32 v70, 14, v122
	v_lshl_add_u32 v70, v123, 10, v70
	v_ashrrev_i32_e32 v71, 31, v70
	v_lshl_add_u64 v[70:71], v[70:71], 2, s[16:17]
	s_or_b64 exec, exec, s[0:1]
	s_waitcnt vmcnt(31)
	v_fmac_f32_e32 v0, 0.5, v50
	v_lshl_add_u64 v[70:71], v[130:131], 2, v[70:71]
	s_and_saveexec_b64 s[0:1], s[10:11]
	s_cbranch_execz .LBB0_5065
	global_store_dword v[70:71], v0, off
